# rec-norm filler loop in P1a software-pipelined (straight-line, two register sets) + split 10240 tokens early, on v19
# baseline (speedup 1.0000x reference)
.LBB0_464:
	s_cmpk_lt_i32 s74, 0x80
	s_cselect_b64 s[0:1], -1, 0
	s_xor_b64 s[4:5], s[92:93], -1
	s_or_b64 s[0:1], s[0:1], s[4:5]
	s_and_b64 vcc, exec, s[0:1]
	s_cbranch_vccnz .LBB0_469
	s_lshl_b32 s0, s74, 9
	v_add_u32_e32 v5, s0, v171
	v_add_u32_e32 v0, 0xffff0000, v5
	s_mov_b32 s0, 0x140000
	v_cmp_gt_i32_e32 vcc, s0, v0
	s_and_saveexec_b64 s[0:1], vcc
	v_readlane_b32 s8, v246, 4
	v_readlane_b32 s18, v246, 14
	v_readlane_b32 s19, v246, 15
	v_readlane_b32 s9, v246, 5
	v_readlane_b32 s10, v246, 6
	v_readlane_b32 s11, v246, 7
	v_readlane_b32 s12, v246, 8
	v_readlane_b32 s13, v246, 9
	v_readlane_b32 s14, v246, 10
	v_readlane_b32 s15, v246, 11
	v_readlane_b32 s16, v246, 12
	v_readlane_b32 s17, v246, 13
	v_readlane_b32 s20, v246, 16
	v_readlane_b32 s21, v246, 17
	v_readlane_b32 s22, v246, 18
	v_readlane_b32 s23, v246, 19
	s_cbranch_execz .LBB0_468
	v_mbcnt_lo_u32_b32 v0, -1, 0
	v_mbcnt_hi_u32_b32 v3, -1, v0
	v_and_b32_e32 v1, 64, v3
	v_xor_b32_e32 v0, 1, v3
	v_add_u32_e32 v4, 64, v1
	v_cmp_lt_i32_e32 vcc, v0, v4
	v_xor_b32_e32 v1, 2, v3
	v_xor_b32_e32 v2, 4, v3
	v_cndmask_b32_e32 v0, v3, v0, vcc
	v_cmp_lt_i32_e32 vcc, v1, v4
	v_xor_b32_e32 v6, 8, v3
	s_add_u32 s4, s76, 0xe000000
	v_cndmask_b32_e32 v1, v3, v1, vcc
	v_cmp_lt_i32_e32 vcc, v2, v4
	s_addc_u32 s5, s77, 0
	v_lshlrev_b32_e32 v0, 2, v0
	v_cndmask_b32_e32 v2, v3, v2, vcc
	v_cmp_lt_i32_e32 vcc, v6, v4
	v_lshlrev_b32_e32 v1, 2, v1
	v_lshlrev_b32_e32 v2, 2, v2
	v_cndmask_b32_e32 v3, v3, v6, vcc
	v_mov_b32_e32 v6, 0xfff80000
	v_lshlrev_b32_e32 v3, 2, v3
	v_add_u32_e32 v4, 0xfffe0000, v5
	v_lshl_add_u32 v5, v5, 3, v6
	s_mov_b64 s[6:7], 0
	v_mov_b32_e32 v6, 0x358637bd
	s_mov_b32 s8, 0x12ffff
	s_and_b64 vcc, exec, s[92:93]
	s_cbranch_vccz .LBB0_467
	v_add_u32_e32 v4, 0x10000, v4
	v_ashrrev_i32_e32 v16, 7, v4
	v_ashrrev_i32_e32 v17, 31, v16
	v_and_b32_e32 v7, 0x3f8, v5
	v_lshlrev_b64 v[16:17], 11, v[16:17]
	v_and_b32_e32 v8, 0x78, v5
	v_lshl_or_b32 v16, v7, 1, v16
	v_lshlrev_b32_e32 v12, 2, v8
	v_lshl_add_u64 v[28:29], s[72:73], 0, v[16:17]
	v_lshl_add_u64 v[20:21], s[4:5], 0, v[16:17]
	v_lshl_add_u64 v[24:25], s[88:89], 0, v[16:17]
	global_load_dwordx4 v[8:11], v12, s[18:19] offset:16
	s_nop 0
	global_load_dwordx4 v[12:15], v12, s[18:19]
	s_nop 0
	global_load_dwordx4 v[16:19], v[28:29], off nt
	s_nop 0
	global_load_dwordx4 v[20:23], v[20:21], off nt
	s_nop 0
	global_load_dwordx4 v[24:27], v[24:25], off nt
	v_add_u32_e32 v5, 0x80000, v5
	v_add_u32_e32 v4, 0x10000, v4
	v_ashrrev_i32_e32 v96, 7, v4
	v_ashrrev_i32_e32 v97, 31, v96
	v_and_b32_e32 v87, 0x3f8, v5
	v_lshlrev_b64 v[96:97], 11, v[96:97]
	v_and_b32_e32 v88, 0x78, v5
	v_lshl_or_b32 v96, v87, 1, v96
	v_lshlrev_b32_e32 v92, 2, v88
	v_lshl_add_u64 v[108:109], s[72:73], 0, v[96:97]
	v_lshl_add_u64 v[100:101], s[4:5], 0, v[96:97]
	v_lshl_add_u64 v[104:105], s[88:89], 0, v[96:97]
	global_load_dwordx4 v[88:91], v92, s[18:19] offset:16
	s_nop 0
	global_load_dwordx4 v[92:95], v92, s[18:19]
	s_nop 0
	global_load_dwordx4 v[96:99], v[108:109], off nt
	s_nop 0
	global_load_dwordx4 v[100:103], v[100:101], off nt
	s_nop 0
	global_load_dwordx4 v[104:107], v[104:105], off nt
	v_add_u32_e32 v5, 0x80000, v5
	s_waitcnt vmcnt(5)
	v_lshlrev_b32_e32 v30, 16, v16
	v_and_b32_e32 v31, 0xffff0000, v16
	v_lshlrev_b32_e32 v16, 16, v17
	v_and_b32_e32 v17, 0xffff0000, v17
	v_lshlrev_b32_e32 v34, 16, v20
	v_and_b32_e32 v35, 0xffff0000, v20
	v_lshlrev_b32_e32 v20, 16, v21
	v_and_b32_e32 v21, 0xffff0000, v21
	v_lshlrev_b32_e32 v32, 16, v18
	v_and_b32_e32 v33, 0xffff0000, v18
	v_lshlrev_b32_e32 v18, 16, v19
	v_and_b32_e32 v19, 0xffff0000, v19
	v_lshlrev_b32_e32 v36, 16, v22
	v_and_b32_e32 v37, 0xffff0000, v22
	v_lshlrev_b32_e32 v22, 16, v23
	v_and_b32_e32 v23, 0xffff0000, v23
	v_pk_add_f32 v[30:31], v[30:31], v[34:35]
	v_pk_add_f32 v[16:17], v[16:17], v[20:21]
	v_pk_add_f32 v[20:21], v[32:33], v[36:37]
	v_pk_add_f32 v[18:19], v[18:19], v[22:23]
	v_pk_mul_f32 v[22:23], v[16:17], v[16:17]
	v_pk_mul_f32 v[32:33], v[30:31], v[30:31]
	v_pk_mul_f32 v[34:35], v[18:19], v[18:19]
	v_pk_mul_f32 v[36:37], v[20:21], v[20:21]
	v_pk_mov_b32 v[42:43], v[32:33], v[22:23] op_sel:[1,0]
	v_mov_b32_e32 v33, v23
	v_mov_b32_e32 v22, v34
	v_mov_b32_e32 v23, v36
	v_mov_b32_e32 v36, v35
	v_pk_add_f32 v[32:33], v[42:43], v[32:33]
	v_pk_add_f32 v[22:23], v[22:23], v[36:37]
	v_add_f32_e32 v7, v32, v33
	v_add_f32_e32 v7, v23, v7
	v_add_f32_e32 v7, v22, v7
	ds_bpermute_b32 v22, v0, v7
	v_lshlrev_b32_e32 v38, 16, v24
	v_and_b32_e32 v39, 0xffff0000, v24
	v_lshlrev_b32_e32 v24, 16, v25
	v_and_b32_e32 v25, 0xffff0000, v25
	s_waitcnt lgkmcnt(0)
	v_add_f32_e32 v7, v7, v22
	ds_bpermute_b32 v22, v1, v7
	v_lshlrev_b32_e32 v40, 16, v26
	v_and_b32_e32 v41, 0xffff0000, v26
	v_lshlrev_b32_e32 v26, 16, v27
	v_and_b32_e32 v27, 0xffff0000, v27
	s_waitcnt lgkmcnt(0)
	v_add_f32_e32 v7, v7, v22
	ds_bpermute_b32 v22, v2, v7
	s_waitcnt lgkmcnt(0)
	v_add_f32_e32 v7, v7, v22
	ds_bpermute_b32 v22, v3, v7
	s_waitcnt lgkmcnt(0)
	v_add_f32_e32 v7, v7, v22
	v_fmamk_f32 v7, v7, 0x3c000000, v6
	v_rsq_f32_e32 v22, v7
	s_nop 0
	v_pk_mul_f32 v[16:17], v[16:17], v[22:23] op_sel_hi:[1,0]
	v_pk_mul_f32 v[30:31], v[30:31], v[22:23] op_sel_hi:[1,0]
	v_pk_mul_f32 v[18:19], v[18:19], v[22:23] op_sel_hi:[1,0]
	v_pk_mul_f32 v[20:21], v[20:21], v[22:23] op_sel_hi:[1,0]
	v_pk_mul_f32 v[12:13], v[12:13], v[30:31]
	v_pk_mul_f32 v[14:15], v[14:15], v[16:17]
	v_pk_mul_f32 v[8:9], v[8:9], v[20:21]
	v_pk_mul_f32 v[10:11], v[10:11], v[18:19]
	v_pk_mul_f32 v[14:15], v[14:15], v[24:25]
	v_pk_mul_f32 v[12:13], v[12:13], v[38:39]
	v_pk_mul_f32 v[16:17], v[10:11], v[26:27]
	v_pk_mul_f32 v[10:11], v[8:9], v[40:41]
	v_cvt_pk_bf16_f32 v8, v12, v13
	v_cvt_pk_bf16_f32 v9, v14, v15
	v_cvt_pk_bf16_f32 v10, v10, v11
	v_cvt_pk_bf16_f32 v11, v16, v17
	global_store_dwordx4 v[28:29], v[8:11], off
	s_nop 1
	v_add_u32_e32 v4, 0x10000, v4
	v_ashrrev_i32_e32 v16, 7, v4
	v_ashrrev_i32_e32 v17, 31, v16
	v_and_b32_e32 v7, 0x3f8, v5
	v_lshlrev_b64 v[16:17], 11, v[16:17]
	v_and_b32_e32 v8, 0x78, v5
	v_lshl_or_b32 v16, v7, 1, v16
	v_lshlrev_b32_e32 v12, 2, v8
	v_lshl_add_u64 v[28:29], s[72:73], 0, v[16:17]
	v_lshl_add_u64 v[20:21], s[4:5], 0, v[16:17]
	v_lshl_add_u64 v[24:25], s[88:89], 0, v[16:17]
	global_load_dwordx4 v[8:11], v12, s[18:19] offset:16
	s_nop 0
	global_load_dwordx4 v[12:15], v12, s[18:19]
	s_nop 0
	global_load_dwordx4 v[16:19], v[28:29], off nt
	s_nop 0
	global_load_dwordx4 v[20:23], v[20:21], off nt
	s_nop 0
	global_load_dwordx4 v[24:27], v[24:25], off nt
	v_add_u32_e32 v5, 0x80000, v5
	s_waitcnt vmcnt(6)
	v_lshlrev_b32_e32 v110, 16, v96
	v_and_b32_e32 v111, 0xffff0000, v96
	v_lshlrev_b32_e32 v96, 16, v97
	v_and_b32_e32 v97, 0xffff0000, v97
	v_lshlrev_b32_e32 v114, 16, v100
	v_and_b32_e32 v115, 0xffff0000, v100
	v_lshlrev_b32_e32 v100, 16, v101
	v_and_b32_e32 v101, 0xffff0000, v101
	v_lshlrev_b32_e32 v112, 16, v98
	v_and_b32_e32 v113, 0xffff0000, v98
	v_lshlrev_b32_e32 v98, 16, v99
	v_and_b32_e32 v99, 0xffff0000, v99
	v_lshlrev_b32_e32 v116, 16, v102
	v_and_b32_e32 v117, 0xffff0000, v102
	v_lshlrev_b32_e32 v102, 16, v103
	v_and_b32_e32 v103, 0xffff0000, v103
	v_pk_add_f32 v[110:111], v[110:111], v[114:115]
	v_pk_add_f32 v[96:97], v[96:97], v[100:101]
	v_pk_add_f32 v[100:101], v[112:113], v[116:117]
	v_pk_add_f32 v[98:99], v[98:99], v[102:103]
	v_pk_mul_f32 v[102:103], v[96:97], v[96:97]
	v_pk_mul_f32 v[112:113], v[110:111], v[110:111]
	v_pk_mul_f32 v[114:115], v[98:99], v[98:99]
	v_pk_mul_f32 v[116:117], v[100:101], v[100:101]
	v_pk_mov_b32 v[122:123], v[112:113], v[102:103] op_sel:[1,0]
	v_mov_b32_e32 v113, v103
	v_mov_b32_e32 v102, v114
	v_mov_b32_e32 v103, v116
	v_mov_b32_e32 v116, v115
	v_pk_add_f32 v[112:113], v[122:123], v[112:113]
	v_pk_add_f32 v[102:103], v[102:103], v[116:117]
	v_add_f32_e32 v87, v112, v113
	v_add_f32_e32 v87, v103, v87
	v_add_f32_e32 v87, v102, v87
	ds_bpermute_b32 v102, v0, v87
	v_lshlrev_b32_e32 v118, 16, v104
	v_and_b32_e32 v119, 0xffff0000, v104
	v_lshlrev_b32_e32 v104, 16, v105
	v_and_b32_e32 v105, 0xffff0000, v105
	s_waitcnt lgkmcnt(0)
	v_add_f32_e32 v87, v87, v102
	ds_bpermute_b32 v102, v1, v87
	v_lshlrev_b32_e32 v120, 16, v106
	v_and_b32_e32 v121, 0xffff0000, v106
	v_lshlrev_b32_e32 v106, 16, v107
	v_and_b32_e32 v107, 0xffff0000, v107
	s_waitcnt lgkmcnt(0)
	v_add_f32_e32 v87, v87, v102
	ds_bpermute_b32 v102, v2, v87
	s_waitcnt lgkmcnt(0)
	v_add_f32_e32 v87, v87, v102
	ds_bpermute_b32 v102, v3, v87
	s_waitcnt lgkmcnt(0)
	v_add_f32_e32 v87, v87, v102
	v_fmamk_f32 v87, v87, 0x3c000000, v6
	v_rsq_f32_e32 v102, v87
	s_nop 0
	v_pk_mul_f32 v[96:97], v[96:97], v[102:103] op_sel_hi:[1,0]
	v_pk_mul_f32 v[110:111], v[110:111], v[102:103] op_sel_hi:[1,0]
	v_pk_mul_f32 v[98:99], v[98:99], v[102:103] op_sel_hi:[1,0]
	v_pk_mul_f32 v[100:101], v[100:101], v[102:103] op_sel_hi:[1,0]
	v_pk_mul_f32 v[92:93], v[92:93], v[110:111]
	v_pk_mul_f32 v[94:95], v[94:95], v[96:97]
	v_pk_mul_f32 v[88:89], v[88:89], v[100:101]
	v_pk_mul_f32 v[90:91], v[90:91], v[98:99]
	v_pk_mul_f32 v[94:95], v[94:95], v[104:105]
	v_pk_mul_f32 v[92:93], v[92:93], v[118:119]
	v_pk_mul_f32 v[96:97], v[90:91], v[106:107]
	v_pk_mul_f32 v[90:91], v[88:89], v[120:121]
	v_cvt_pk_bf16_f32 v88, v92, v93
	v_cvt_pk_bf16_f32 v89, v94, v95
	v_cvt_pk_bf16_f32 v90, v90, v91
	v_cvt_pk_bf16_f32 v91, v96, v97
	global_store_dwordx4 v[108:109], v[88:91], off
	s_nop 1
	v_add_u32_e32 v4, 0x10000, v4
	v_ashrrev_i32_e32 v96, 7, v4
	v_ashrrev_i32_e32 v97, 31, v96
	v_and_b32_e32 v87, 0x3f8, v5
	v_lshlrev_b64 v[96:97], 11, v[96:97]
	v_and_b32_e32 v88, 0x78, v5
	v_lshl_or_b32 v96, v87, 1, v96
	v_lshlrev_b32_e32 v92, 2, v88
	v_lshl_add_u64 v[108:109], s[72:73], 0, v[96:97]
	v_lshl_add_u64 v[100:101], s[4:5], 0, v[96:97]
	v_lshl_add_u64 v[104:105], s[88:89], 0, v[96:97]
	global_load_dwordx4 v[88:91], v92, s[18:19] offset:16
	s_nop 0
	global_load_dwordx4 v[92:95], v92, s[18:19]
	s_nop 0
	global_load_dwordx4 v[96:99], v[108:109], off nt
	s_nop 0
	global_load_dwordx4 v[100:103], v[100:101], off nt
	s_nop 0
	global_load_dwordx4 v[104:107], v[104:105], off nt
	v_add_u32_e32 v5, 0x80000, v5
	s_waitcnt vmcnt(6)
	v_lshlrev_b32_e32 v30, 16, v16
	v_and_b32_e32 v31, 0xffff0000, v16
	v_lshlrev_b32_e32 v16, 16, v17
	v_and_b32_e32 v17, 0xffff0000, v17
	v_lshlrev_b32_e32 v34, 16, v20
	v_and_b32_e32 v35, 0xffff0000, v20
	v_lshlrev_b32_e32 v20, 16, v21
	v_and_b32_e32 v21, 0xffff0000, v21
	v_lshlrev_b32_e32 v32, 16, v18
	v_and_b32_e32 v33, 0xffff0000, v18
	v_lshlrev_b32_e32 v18, 16, v19
	v_and_b32_e32 v19, 0xffff0000, v19
	v_lshlrev_b32_e32 v36, 16, v22
	v_and_b32_e32 v37, 0xffff0000, v22
	v_lshlrev_b32_e32 v22, 16, v23
	v_and_b32_e32 v23, 0xffff0000, v23
	v_pk_add_f32 v[30:31], v[30:31], v[34:35]
	v_pk_add_f32 v[16:17], v[16:17], v[20:21]
	v_pk_add_f32 v[20:21], v[32:33], v[36:37]
	v_pk_add_f32 v[18:19], v[18:19], v[22:23]
	v_pk_mul_f32 v[22:23], v[16:17], v[16:17]
	v_pk_mul_f32 v[32:33], v[30:31], v[30:31]
	v_pk_mul_f32 v[34:35], v[18:19], v[18:19]
	v_pk_mul_f32 v[36:37], v[20:21], v[20:21]
	v_pk_mov_b32 v[42:43], v[32:33], v[22:23] op_sel:[1,0]
	v_mov_b32_e32 v33, v23
	v_mov_b32_e32 v22, v34
	v_mov_b32_e32 v23, v36
	v_mov_b32_e32 v36, v35
	v_pk_add_f32 v[32:33], v[42:43], v[32:33]
	v_pk_add_f32 v[22:23], v[22:23], v[36:37]
	v_add_f32_e32 v7, v32, v33
	v_add_f32_e32 v7, v23, v7
	v_add_f32_e32 v7, v22, v7
	ds_bpermute_b32 v22, v0, v7
	v_lshlrev_b32_e32 v38, 16, v24
	v_and_b32_e32 v39, 0xffff0000, v24
	v_lshlrev_b32_e32 v24, 16, v25
	v_and_b32_e32 v25, 0xffff0000, v25
	s_waitcnt lgkmcnt(0)
	v_add_f32_e32 v7, v7, v22
	ds_bpermute_b32 v22, v1, v7
	v_lshlrev_b32_e32 v40, 16, v26
	v_and_b32_e32 v41, 0xffff0000, v26
	v_lshlrev_b32_e32 v26, 16, v27
	v_and_b32_e32 v27, 0xffff0000, v27
	s_waitcnt lgkmcnt(0)
	v_add_f32_e32 v7, v7, v22
	ds_bpermute_b32 v22, v2, v7
	s_waitcnt lgkmcnt(0)
	v_add_f32_e32 v7, v7, v22
	ds_bpermute_b32 v22, v3, v7
	s_waitcnt lgkmcnt(0)
	v_add_f32_e32 v7, v7, v22
	v_fmamk_f32 v7, v7, 0x3c000000, v6
	v_rsq_f32_e32 v22, v7
	s_nop 0
	v_pk_mul_f32 v[16:17], v[16:17], v[22:23] op_sel_hi:[1,0]
	v_pk_mul_f32 v[30:31], v[30:31], v[22:23] op_sel_hi:[1,0]
	v_pk_mul_f32 v[18:19], v[18:19], v[22:23] op_sel_hi:[1,0]
	v_pk_mul_f32 v[20:21], v[20:21], v[22:23] op_sel_hi:[1,0]
	v_pk_mul_f32 v[12:13], v[12:13], v[30:31]
	v_pk_mul_f32 v[14:15], v[14:15], v[16:17]
	v_pk_mul_f32 v[8:9], v[8:9], v[20:21]
	v_pk_mul_f32 v[10:11], v[10:11], v[18:19]
	v_pk_mul_f32 v[14:15], v[14:15], v[24:25]
	v_pk_mul_f32 v[12:13], v[12:13], v[38:39]
	v_pk_mul_f32 v[16:17], v[10:11], v[26:27]
	v_pk_mul_f32 v[10:11], v[8:9], v[40:41]
	v_cvt_pk_bf16_f32 v8, v12, v13
	v_cvt_pk_bf16_f32 v9, v14, v15
	v_cvt_pk_bf16_f32 v10, v10, v11
	v_cvt_pk_bf16_f32 v11, v16, v17
	global_store_dwordx4 v[28:29], v[8:11], off
	s_nop 1
	v_add_u32_e32 v4, 0x10000, v4
	v_ashrrev_i32_e32 v16, 7, v4
	v_ashrrev_i32_e32 v17, 31, v16
	v_and_b32_e32 v7, 0x3f8, v5
	v_lshlrev_b64 v[16:17], 11, v[16:17]
	v_and_b32_e32 v8, 0x78, v5
	v_lshl_or_b32 v16, v7, 1, v16
	v_lshlrev_b32_e32 v12, 2, v8
	v_lshl_add_u64 v[28:29], s[72:73], 0, v[16:17]
	v_lshl_add_u64 v[20:21], s[4:5], 0, v[16:17]
	v_lshl_add_u64 v[24:25], s[88:89], 0, v[16:17]
	global_load_dwordx4 v[8:11], v12, s[18:19] offset:16
	s_nop 0
	global_load_dwordx4 v[12:15], v12, s[18:19]
	s_nop 0
	global_load_dwordx4 v[16:19], v[28:29], off nt
	s_nop 0
	global_load_dwordx4 v[20:23], v[20:21], off nt
	s_nop 0
	global_load_dwordx4 v[24:27], v[24:25], off nt
	v_add_u32_e32 v5, 0x80000, v5
	s_waitcnt vmcnt(6)
	v_lshlrev_b32_e32 v110, 16, v96
	v_and_b32_e32 v111, 0xffff0000, v96
	v_lshlrev_b32_e32 v96, 16, v97
	v_and_b32_e32 v97, 0xffff0000, v97
	v_lshlrev_b32_e32 v114, 16, v100
	v_and_b32_e32 v115, 0xffff0000, v100
	v_lshlrev_b32_e32 v100, 16, v101
	v_and_b32_e32 v101, 0xffff0000, v101
	v_lshlrev_b32_e32 v112, 16, v98
	v_and_b32_e32 v113, 0xffff0000, v98
	v_lshlrev_b32_e32 v98, 16, v99
	v_and_b32_e32 v99, 0xffff0000, v99
	v_lshlrev_b32_e32 v116, 16, v102
	v_and_b32_e32 v117, 0xffff0000, v102
	v_lshlrev_b32_e32 v102, 16, v103
	v_and_b32_e32 v103, 0xffff0000, v103
	v_pk_add_f32 v[110:111], v[110:111], v[114:115]
	v_pk_add_f32 v[96:97], v[96:97], v[100:101]
	v_pk_add_f32 v[100:101], v[112:113], v[116:117]
	v_pk_add_f32 v[98:99], v[98:99], v[102:103]
	v_pk_mul_f32 v[102:103], v[96:97], v[96:97]
	v_pk_mul_f32 v[112:113], v[110:111], v[110:111]
	v_pk_mul_f32 v[114:115], v[98:99], v[98:99]
	v_pk_mul_f32 v[116:117], v[100:101], v[100:101]
	v_pk_mov_b32 v[122:123], v[112:113], v[102:103] op_sel:[1,0]
	v_mov_b32_e32 v113, v103
	v_mov_b32_e32 v102, v114
	v_mov_b32_e32 v103, v116
	v_mov_b32_e32 v116, v115
	v_pk_add_f32 v[112:113], v[122:123], v[112:113]
	v_pk_add_f32 v[102:103], v[102:103], v[116:117]
	v_add_f32_e32 v87, v112, v113
	v_add_f32_e32 v87, v103, v87
	v_add_f32_e32 v87, v102, v87
	ds_bpermute_b32 v102, v0, v87
	v_lshlrev_b32_e32 v118, 16, v104
	v_and_b32_e32 v119, 0xffff0000, v104
	v_lshlrev_b32_e32 v104, 16, v105
	v_and_b32_e32 v105, 0xffff0000, v105
	s_waitcnt lgkmcnt(0)
	v_add_f32_e32 v87, v87, v102
	ds_bpermute_b32 v102, v1, v87
	v_lshlrev_b32_e32 v120, 16, v106
	v_and_b32_e32 v121, 0xffff0000, v106
	v_lshlrev_b32_e32 v106, 16, v107
	v_and_b32_e32 v107, 0xffff0000, v107
	s_waitcnt lgkmcnt(0)
	v_add_f32_e32 v87, v87, v102
	ds_bpermute_b32 v102, v2, v87
	s_waitcnt lgkmcnt(0)
	v_add_f32_e32 v87, v87, v102
	ds_bpermute_b32 v102, v3, v87
	s_waitcnt lgkmcnt(0)
	v_add_f32_e32 v87, v87, v102
	v_fmamk_f32 v87, v87, 0x3c000000, v6
	v_rsq_f32_e32 v102, v87
	s_nop 0
	v_pk_mul_f32 v[96:97], v[96:97], v[102:103] op_sel_hi:[1,0]
	v_pk_mul_f32 v[110:111], v[110:111], v[102:103] op_sel_hi:[1,0]
	v_pk_mul_f32 v[98:99], v[98:99], v[102:103] op_sel_hi:[1,0]
	v_pk_mul_f32 v[100:101], v[100:101], v[102:103] op_sel_hi:[1,0]
	v_pk_mul_f32 v[92:93], v[92:93], v[110:111]
	v_pk_mul_f32 v[94:95], v[94:95], v[96:97]
	v_pk_mul_f32 v[88:89], v[88:89], v[100:101]
	v_pk_mul_f32 v[90:91], v[90:91], v[98:99]
	v_pk_mul_f32 v[94:95], v[94:95], v[104:105]
	v_pk_mul_f32 v[92:93], v[92:93], v[118:119]
	v_pk_mul_f32 v[96:97], v[90:91], v[106:107]
	v_pk_mul_f32 v[90:91], v[88:89], v[120:121]
	v_cvt_pk_bf16_f32 v88, v92, v93
	v_cvt_pk_bf16_f32 v89, v94, v95
	v_cvt_pk_bf16_f32 v90, v90, v91
	v_cvt_pk_bf16_f32 v91, v96, v97
	global_store_dwordx4 v[108:109], v[88:91], off
	s_nop 1
	v_add_u32_e32 v4, 0x10000, v4
	v_ashrrev_i32_e32 v96, 7, v4
	v_ashrrev_i32_e32 v97, 31, v96
	v_and_b32_e32 v87, 0x3f8, v5
	v_lshlrev_b64 v[96:97], 11, v[96:97]
	v_and_b32_e32 v88, 0x78, v5
	v_lshl_or_b32 v96, v87, 1, v96
	v_lshlrev_b32_e32 v92, 2, v88
	v_lshl_add_u64 v[108:109], s[72:73], 0, v[96:97]
	v_lshl_add_u64 v[100:101], s[4:5], 0, v[96:97]
	v_lshl_add_u64 v[104:105], s[88:89], 0, v[96:97]
	global_load_dwordx4 v[88:91], v92, s[18:19] offset:16
	s_nop 0
	global_load_dwordx4 v[92:95], v92, s[18:19]
	s_nop 0
	global_load_dwordx4 v[96:99], v[108:109], off nt
	s_nop 0
	global_load_dwordx4 v[100:103], v[100:101], off nt
	s_nop 0
	global_load_dwordx4 v[104:107], v[104:105], off nt
	v_add_u32_e32 v5, 0x80000, v5
	s_waitcnt vmcnt(6)
	v_lshlrev_b32_e32 v30, 16, v16
	v_and_b32_e32 v31, 0xffff0000, v16
	v_lshlrev_b32_e32 v16, 16, v17
	v_and_b32_e32 v17, 0xffff0000, v17
	v_lshlrev_b32_e32 v34, 16, v20
	v_and_b32_e32 v35, 0xffff0000, v20
	v_lshlrev_b32_e32 v20, 16, v21
	v_and_b32_e32 v21, 0xffff0000, v21
	v_lshlrev_b32_e32 v32, 16, v18
	v_and_b32_e32 v33, 0xffff0000, v18
	v_lshlrev_b32_e32 v18, 16, v19
	v_and_b32_e32 v19, 0xffff0000, v19
	v_lshlrev_b32_e32 v36, 16, v22
	v_and_b32_e32 v37, 0xffff0000, v22
	v_lshlrev_b32_e32 v22, 16, v23
	v_and_b32_e32 v23, 0xffff0000, v23
	v_pk_add_f32 v[30:31], v[30:31], v[34:35]
	v_pk_add_f32 v[16:17], v[16:17], v[20:21]
	v_pk_add_f32 v[20:21], v[32:33], v[36:37]
	v_pk_add_f32 v[18:19], v[18:19], v[22:23]
	v_pk_mul_f32 v[22:23], v[16:17], v[16:17]
	v_pk_mul_f32 v[32:33], v[30:31], v[30:31]
	v_pk_mul_f32 v[34:35], v[18:19], v[18:19]
	v_pk_mul_f32 v[36:37], v[20:21], v[20:21]
	v_pk_mov_b32 v[42:43], v[32:33], v[22:23] op_sel:[1,0]
	v_mov_b32_e32 v33, v23
	v_mov_b32_e32 v22, v34
	v_mov_b32_e32 v23, v36
	v_mov_b32_e32 v36, v35
	v_pk_add_f32 v[32:33], v[42:43], v[32:33]
	v_pk_add_f32 v[22:23], v[22:23], v[36:37]
	v_add_f32_e32 v7, v32, v33
	v_add_f32_e32 v7, v23, v7
	v_add_f32_e32 v7, v22, v7
	ds_bpermute_b32 v22, v0, v7
	v_lshlrev_b32_e32 v38, 16, v24
	v_and_b32_e32 v39, 0xffff0000, v24
	v_lshlrev_b32_e32 v24, 16, v25
	v_and_b32_e32 v25, 0xffff0000, v25
	s_waitcnt lgkmcnt(0)
	v_add_f32_e32 v7, v7, v22
	ds_bpermute_b32 v22, v1, v7
	v_lshlrev_b32_e32 v40, 16, v26
	v_and_b32_e32 v41, 0xffff0000, v26
	v_lshlrev_b32_e32 v26, 16, v27
	v_and_b32_e32 v27, 0xffff0000, v27
	s_waitcnt lgkmcnt(0)
	v_add_f32_e32 v7, v7, v22
	ds_bpermute_b32 v22, v2, v7
	s_waitcnt lgkmcnt(0)
	v_add_f32_e32 v7, v7, v22
	ds_bpermute_b32 v22, v3, v7
	s_waitcnt lgkmcnt(0)
	v_add_f32_e32 v7, v7, v22
	v_fmamk_f32 v7, v7, 0x3c000000, v6
	v_rsq_f32_e32 v22, v7
	s_nop 0
	v_pk_mul_f32 v[16:17], v[16:17], v[22:23] op_sel_hi:[1,0]
	v_pk_mul_f32 v[30:31], v[30:31], v[22:23] op_sel_hi:[1,0]
	v_pk_mul_f32 v[18:19], v[18:19], v[22:23] op_sel_hi:[1,0]
	v_pk_mul_f32 v[20:21], v[20:21], v[22:23] op_sel_hi:[1,0]
	v_pk_mul_f32 v[12:13], v[12:13], v[30:31]
	v_pk_mul_f32 v[14:15], v[14:15], v[16:17]
	v_pk_mul_f32 v[8:9], v[8:9], v[20:21]
	v_pk_mul_f32 v[10:11], v[10:11], v[18:19]
	v_pk_mul_f32 v[14:15], v[14:15], v[24:25]
	v_pk_mul_f32 v[12:13], v[12:13], v[38:39]
	v_pk_mul_f32 v[16:17], v[10:11], v[26:27]
	v_pk_mul_f32 v[10:11], v[8:9], v[40:41]
	v_cvt_pk_bf16_f32 v8, v12, v13
	v_cvt_pk_bf16_f32 v9, v14, v15
	v_cvt_pk_bf16_f32 v10, v10, v11
	v_cvt_pk_bf16_f32 v11, v16, v17
	global_store_dwordx4 v[28:29], v[8:11], off
	s_nop 1
	v_add_u32_e32 v4, 0x10000, v4
	v_ashrrev_i32_e32 v16, 7, v4
	v_ashrrev_i32_e32 v17, 31, v16
	v_and_b32_e32 v7, 0x3f8, v5
	v_lshlrev_b64 v[16:17], 11, v[16:17]
	v_and_b32_e32 v8, 0x78, v5
	v_lshl_or_b32 v16, v7, 1, v16
	v_lshlrev_b32_e32 v12, 2, v8
	v_lshl_add_u64 v[28:29], s[72:73], 0, v[16:17]
	v_lshl_add_u64 v[20:21], s[4:5], 0, v[16:17]
	v_lshl_add_u64 v[24:25], s[88:89], 0, v[16:17]
	global_load_dwordx4 v[8:11], v12, s[18:19] offset:16
	s_nop 0
	global_load_dwordx4 v[12:15], v12, s[18:19]
	s_nop 0
	global_load_dwordx4 v[16:19], v[28:29], off nt
	s_nop 0
	global_load_dwordx4 v[20:23], v[20:21], off nt
	s_nop 0
	global_load_dwordx4 v[24:27], v[24:25], off nt
	v_add_u32_e32 v5, 0x80000, v5
	s_waitcnt vmcnt(6)
	v_lshlrev_b32_e32 v110, 16, v96
	v_and_b32_e32 v111, 0xffff0000, v96
	v_lshlrev_b32_e32 v96, 16, v97
	v_and_b32_e32 v97, 0xffff0000, v97
	v_lshlrev_b32_e32 v114, 16, v100
	v_and_b32_e32 v115, 0xffff0000, v100
	v_lshlrev_b32_e32 v100, 16, v101
	v_and_b32_e32 v101, 0xffff0000, v101
	v_lshlrev_b32_e32 v112, 16, v98
	v_and_b32_e32 v113, 0xffff0000, v98
	v_lshlrev_b32_e32 v98, 16, v99
	v_and_b32_e32 v99, 0xffff0000, v99
	v_lshlrev_b32_e32 v116, 16, v102
	v_and_b32_e32 v117, 0xffff0000, v102
	v_lshlrev_b32_e32 v102, 16, v103
	v_and_b32_e32 v103, 0xffff0000, v103
	v_pk_add_f32 v[110:111], v[110:111], v[114:115]
	v_pk_add_f32 v[96:97], v[96:97], v[100:101]
	v_pk_add_f32 v[100:101], v[112:113], v[116:117]
	v_pk_add_f32 v[98:99], v[98:99], v[102:103]
	v_pk_mul_f32 v[102:103], v[96:97], v[96:97]
	v_pk_mul_f32 v[112:113], v[110:111], v[110:111]
	v_pk_mul_f32 v[114:115], v[98:99], v[98:99]
	v_pk_mul_f32 v[116:117], v[100:101], v[100:101]
	v_pk_mov_b32 v[122:123], v[112:113], v[102:103] op_sel:[1,0]
	v_mov_b32_e32 v113, v103
	v_mov_b32_e32 v102, v114
	v_mov_b32_e32 v103, v116
	v_mov_b32_e32 v116, v115
	v_pk_add_f32 v[112:113], v[122:123], v[112:113]
	v_pk_add_f32 v[102:103], v[102:103], v[116:117]
	v_add_f32_e32 v87, v112, v113
	v_add_f32_e32 v87, v103, v87
	v_add_f32_e32 v87, v102, v87
	ds_bpermute_b32 v102, v0, v87
	v_lshlrev_b32_e32 v118, 16, v104
	v_and_b32_e32 v119, 0xffff0000, v104
	v_lshlrev_b32_e32 v104, 16, v105
	v_and_b32_e32 v105, 0xffff0000, v105
	s_waitcnt lgkmcnt(0)
	v_add_f32_e32 v87, v87, v102
	ds_bpermute_b32 v102, v1, v87
	v_lshlrev_b32_e32 v120, 16, v106
	v_and_b32_e32 v121, 0xffff0000, v106
	v_lshlrev_b32_e32 v106, 16, v107
	v_and_b32_e32 v107, 0xffff0000, v107
	s_waitcnt lgkmcnt(0)
	v_add_f32_e32 v87, v87, v102
	ds_bpermute_b32 v102, v2, v87
	s_waitcnt lgkmcnt(0)
	v_add_f32_e32 v87, v87, v102
	ds_bpermute_b32 v102, v3, v87
	s_waitcnt lgkmcnt(0)
	v_add_f32_e32 v87, v87, v102
	v_fmamk_f32 v87, v87, 0x3c000000, v6
	v_rsq_f32_e32 v102, v87
	s_nop 0
	v_pk_mul_f32 v[96:97], v[96:97], v[102:103] op_sel_hi:[1,0]
	v_pk_mul_f32 v[110:111], v[110:111], v[102:103] op_sel_hi:[1,0]
	v_pk_mul_f32 v[98:99], v[98:99], v[102:103] op_sel_hi:[1,0]
	v_pk_mul_f32 v[100:101], v[100:101], v[102:103] op_sel_hi:[1,0]
	v_pk_mul_f32 v[92:93], v[92:93], v[110:111]
	v_pk_mul_f32 v[94:95], v[94:95], v[96:97]
	v_pk_mul_f32 v[88:89], v[88:89], v[100:101]
	v_pk_mul_f32 v[90:91], v[90:91], v[98:99]
	v_pk_mul_f32 v[94:95], v[94:95], v[104:105]
	v_pk_mul_f32 v[92:93], v[92:93], v[118:119]
	v_pk_mul_f32 v[96:97], v[90:91], v[106:107]
	v_pk_mul_f32 v[90:91], v[88:89], v[120:121]
	v_cvt_pk_bf16_f32 v88, v92, v93
	v_cvt_pk_bf16_f32 v89, v94, v95
	v_cvt_pk_bf16_f32 v90, v90, v91
	v_cvt_pk_bf16_f32 v91, v96, v97
	global_store_dwordx4 v[108:109], v[88:91], off
	s_nop 1
	v_add_u32_e32 v4, 0x10000, v4
	v_ashrrev_i32_e32 v96, 7, v4
	v_ashrrev_i32_e32 v97, 31, v96
	v_and_b32_e32 v87, 0x3f8, v5
	v_lshlrev_b64 v[96:97], 11, v[96:97]
	v_and_b32_e32 v88, 0x78, v5
	v_lshl_or_b32 v96, v87, 1, v96
	v_lshlrev_b32_e32 v92, 2, v88
	v_lshl_add_u64 v[108:109], s[72:73], 0, v[96:97]
	v_lshl_add_u64 v[100:101], s[4:5], 0, v[96:97]
	v_lshl_add_u64 v[104:105], s[88:89], 0, v[96:97]
	global_load_dwordx4 v[88:91], v92, s[18:19] offset:16
	s_nop 0
	global_load_dwordx4 v[92:95], v92, s[18:19]
	s_nop 0
	global_load_dwordx4 v[96:99], v[108:109], off nt
	s_nop 0
	global_load_dwordx4 v[100:103], v[100:101], off nt
	s_nop 0
	global_load_dwordx4 v[104:107], v[104:105], off nt
	v_add_u32_e32 v5, 0x80000, v5
	s_waitcnt vmcnt(6)
	v_lshlrev_b32_e32 v30, 16, v16
	v_and_b32_e32 v31, 0xffff0000, v16
	v_lshlrev_b32_e32 v16, 16, v17
	v_and_b32_e32 v17, 0xffff0000, v17
	v_lshlrev_b32_e32 v34, 16, v20
	v_and_b32_e32 v35, 0xffff0000, v20
	v_lshlrev_b32_e32 v20, 16, v21
	v_and_b32_e32 v21, 0xffff0000, v21
	v_lshlrev_b32_e32 v32, 16, v18
	v_and_b32_e32 v33, 0xffff0000, v18
	v_lshlrev_b32_e32 v18, 16, v19
	v_and_b32_e32 v19, 0xffff0000, v19
	v_lshlrev_b32_e32 v36, 16, v22
	v_and_b32_e32 v37, 0xffff0000, v22
	v_lshlrev_b32_e32 v22, 16, v23
	v_and_b32_e32 v23, 0xffff0000, v23
	v_pk_add_f32 v[30:31], v[30:31], v[34:35]
	v_pk_add_f32 v[16:17], v[16:17], v[20:21]
	v_pk_add_f32 v[20:21], v[32:33], v[36:37]
	v_pk_add_f32 v[18:19], v[18:19], v[22:23]
	v_pk_mul_f32 v[22:23], v[16:17], v[16:17]
	v_pk_mul_f32 v[32:33], v[30:31], v[30:31]
	v_pk_mul_f32 v[34:35], v[18:19], v[18:19]
	v_pk_mul_f32 v[36:37], v[20:21], v[20:21]
	v_pk_mov_b32 v[42:43], v[32:33], v[22:23] op_sel:[1,0]
	v_mov_b32_e32 v33, v23
	v_mov_b32_e32 v22, v34
	v_mov_b32_e32 v23, v36
	v_mov_b32_e32 v36, v35
	v_pk_add_f32 v[32:33], v[42:43], v[32:33]
	v_pk_add_f32 v[22:23], v[22:23], v[36:37]
	v_add_f32_e32 v7, v32, v33
	v_add_f32_e32 v7, v23, v7
	v_add_f32_e32 v7, v22, v7
	ds_bpermute_b32 v22, v0, v7
	v_lshlrev_b32_e32 v38, 16, v24
	v_and_b32_e32 v39, 0xffff0000, v24
	v_lshlrev_b32_e32 v24, 16, v25
	v_and_b32_e32 v25, 0xffff0000, v25
	s_waitcnt lgkmcnt(0)
	v_add_f32_e32 v7, v7, v22
	ds_bpermute_b32 v22, v1, v7
	v_lshlrev_b32_e32 v40, 16, v26
	v_and_b32_e32 v41, 0xffff0000, v26
	v_lshlrev_b32_e32 v26, 16, v27
	v_and_b32_e32 v27, 0xffff0000, v27
	s_waitcnt lgkmcnt(0)
	v_add_f32_e32 v7, v7, v22
	ds_bpermute_b32 v22, v2, v7
	s_waitcnt lgkmcnt(0)
	v_add_f32_e32 v7, v7, v22
	ds_bpermute_b32 v22, v3, v7
	s_waitcnt lgkmcnt(0)
	v_add_f32_e32 v7, v7, v22
	v_fmamk_f32 v7, v7, 0x3c000000, v6
	v_rsq_f32_e32 v22, v7
	s_nop 0
	v_pk_mul_f32 v[16:17], v[16:17], v[22:23] op_sel_hi:[1,0]
	v_pk_mul_f32 v[30:31], v[30:31], v[22:23] op_sel_hi:[1,0]
	v_pk_mul_f32 v[18:19], v[18:19], v[22:23] op_sel_hi:[1,0]
	v_pk_mul_f32 v[20:21], v[20:21], v[22:23] op_sel_hi:[1,0]
	v_pk_mul_f32 v[12:13], v[12:13], v[30:31]
	v_pk_mul_f32 v[14:15], v[14:15], v[16:17]
	v_pk_mul_f32 v[8:9], v[8:9], v[20:21]
	v_pk_mul_f32 v[10:11], v[10:11], v[18:19]
	v_pk_mul_f32 v[14:15], v[14:15], v[24:25]
	v_pk_mul_f32 v[12:13], v[12:13], v[38:39]
	v_pk_mul_f32 v[16:17], v[10:11], v[26:27]
	v_pk_mul_f32 v[10:11], v[8:9], v[40:41]
	v_cvt_pk_bf16_f32 v8, v12, v13
	v_cvt_pk_bf16_f32 v9, v14, v15
	v_cvt_pk_bf16_f32 v10, v10, v11
	v_cvt_pk_bf16_f32 v11, v16, v17
	global_store_dwordx4 v[28:29], v[8:11], off
	s_nop 1
	v_add_u32_e32 v4, 0x10000, v4
	v_ashrrev_i32_e32 v16, 7, v4
	v_ashrrev_i32_e32 v17, 31, v16
	v_and_b32_e32 v7, 0x3f8, v5
	v_lshlrev_b64 v[16:17], 11, v[16:17]
	v_and_b32_e32 v8, 0x78, v5
	v_lshl_or_b32 v16, v7, 1, v16
	v_lshlrev_b32_e32 v12, 2, v8
	v_lshl_add_u64 v[28:29], s[72:73], 0, v[16:17]
	v_lshl_add_u64 v[20:21], s[4:5], 0, v[16:17]
	v_lshl_add_u64 v[24:25], s[88:89], 0, v[16:17]
	global_load_dwordx4 v[8:11], v12, s[18:19] offset:16
	s_nop 0
	global_load_dwordx4 v[12:15], v12, s[18:19]
	s_nop 0
	global_load_dwordx4 v[16:19], v[28:29], off nt
	s_nop 0
	global_load_dwordx4 v[20:23], v[20:21], off nt
	s_nop 0
	global_load_dwordx4 v[24:27], v[24:25], off nt
	v_add_u32_e32 v5, 0x80000, v5
	s_waitcnt vmcnt(6)
	v_lshlrev_b32_e32 v110, 16, v96
	v_and_b32_e32 v111, 0xffff0000, v96
	v_lshlrev_b32_e32 v96, 16, v97
	v_and_b32_e32 v97, 0xffff0000, v97
	v_lshlrev_b32_e32 v114, 16, v100
	v_and_b32_e32 v115, 0xffff0000, v100
	v_lshlrev_b32_e32 v100, 16, v101
	v_and_b32_e32 v101, 0xffff0000, v101
	v_lshlrev_b32_e32 v112, 16, v98
	v_and_b32_e32 v113, 0xffff0000, v98
	v_lshlrev_b32_e32 v98, 16, v99
	v_and_b32_e32 v99, 0xffff0000, v99
	v_lshlrev_b32_e32 v116, 16, v102
	v_and_b32_e32 v117, 0xffff0000, v102
	v_lshlrev_b32_e32 v102, 16, v103
	v_and_b32_e32 v103, 0xffff0000, v103
	v_pk_add_f32 v[110:111], v[110:111], v[114:115]
	v_pk_add_f32 v[96:97], v[96:97], v[100:101]
	v_pk_add_f32 v[100:101], v[112:113], v[116:117]
	v_pk_add_f32 v[98:99], v[98:99], v[102:103]
	v_pk_mul_f32 v[102:103], v[96:97], v[96:97]
	v_pk_mul_f32 v[112:113], v[110:111], v[110:111]
	v_pk_mul_f32 v[114:115], v[98:99], v[98:99]
	v_pk_mul_f32 v[116:117], v[100:101], v[100:101]
	v_pk_mov_b32 v[122:123], v[112:113], v[102:103] op_sel:[1,0]
	v_mov_b32_e32 v113, v103
	v_mov_b32_e32 v102, v114
	v_mov_b32_e32 v103, v116
	v_mov_b32_e32 v116, v115
	v_pk_add_f32 v[112:113], v[122:123], v[112:113]
	v_pk_add_f32 v[102:103], v[102:103], v[116:117]
	v_add_f32_e32 v87, v112, v113
	v_add_f32_e32 v87, v103, v87
	v_add_f32_e32 v87, v102, v87
	ds_bpermute_b32 v102, v0, v87
	v_lshlrev_b32_e32 v118, 16, v104
	v_and_b32_e32 v119, 0xffff0000, v104
	v_lshlrev_b32_e32 v104, 16, v105
	v_and_b32_e32 v105, 0xffff0000, v105
	s_waitcnt lgkmcnt(0)
	v_add_f32_e32 v87, v87, v102
	ds_bpermute_b32 v102, v1, v87
	v_lshlrev_b32_e32 v120, 16, v106
	v_and_b32_e32 v121, 0xffff0000, v106
	v_lshlrev_b32_e32 v106, 16, v107
	v_and_b32_e32 v107, 0xffff0000, v107
	s_waitcnt lgkmcnt(0)
	v_add_f32_e32 v87, v87, v102
	ds_bpermute_b32 v102, v2, v87
	s_waitcnt lgkmcnt(0)
	v_add_f32_e32 v87, v87, v102
	ds_bpermute_b32 v102, v3, v87
	s_waitcnt lgkmcnt(0)
	v_add_f32_e32 v87, v87, v102
	v_fmamk_f32 v87, v87, 0x3c000000, v6
	v_rsq_f32_e32 v102, v87
	s_nop 0
	v_pk_mul_f32 v[96:97], v[96:97], v[102:103] op_sel_hi:[1,0]
	v_pk_mul_f32 v[110:111], v[110:111], v[102:103] op_sel_hi:[1,0]
	v_pk_mul_f32 v[98:99], v[98:99], v[102:103] op_sel_hi:[1,0]
	v_pk_mul_f32 v[100:101], v[100:101], v[102:103] op_sel_hi:[1,0]
	v_pk_mul_f32 v[92:93], v[92:93], v[110:111]
	v_pk_mul_f32 v[94:95], v[94:95], v[96:97]
	v_pk_mul_f32 v[88:89], v[88:89], v[100:101]
	v_pk_mul_f32 v[90:91], v[90:91], v[98:99]
	v_pk_mul_f32 v[94:95], v[94:95], v[104:105]
	v_pk_mul_f32 v[92:93], v[92:93], v[118:119]
	v_pk_mul_f32 v[96:97], v[90:91], v[106:107]
	v_pk_mul_f32 v[90:91], v[88:89], v[120:121]
	v_cvt_pk_bf16_f32 v88, v92, v93
	v_cvt_pk_bf16_f32 v89, v94, v95
	v_cvt_pk_bf16_f32 v90, v90, v91
	v_cvt_pk_bf16_f32 v91, v96, v97
	global_store_dwordx4 v[108:109], v[88:91], off
	s_nop 1
	v_add_u32_e32 v4, 0x10000, v4
	v_ashrrev_i32_e32 v96, 7, v4
	v_ashrrev_i32_e32 v97, 31, v96
	v_and_b32_e32 v87, 0x3f8, v5
	v_lshlrev_b64 v[96:97], 11, v[96:97]
	v_and_b32_e32 v88, 0x78, v5
	v_lshl_or_b32 v96, v87, 1, v96
	v_lshlrev_b32_e32 v92, 2, v88
	v_lshl_add_u64 v[108:109], s[72:73], 0, v[96:97]
	v_lshl_add_u64 v[100:101], s[4:5], 0, v[96:97]
	v_lshl_add_u64 v[104:105], s[88:89], 0, v[96:97]
	global_load_dwordx4 v[88:91], v92, s[18:19] offset:16
	s_nop 0
	global_load_dwordx4 v[92:95], v92, s[18:19]
	s_nop 0
	global_load_dwordx4 v[96:99], v[108:109], off nt
	s_nop 0
	global_load_dwordx4 v[100:103], v[100:101], off nt
	s_nop 0
	global_load_dwordx4 v[104:107], v[104:105], off nt
	v_add_u32_e32 v5, 0x80000, v5
	s_waitcnt vmcnt(6)
	v_lshlrev_b32_e32 v30, 16, v16
	v_and_b32_e32 v31, 0xffff0000, v16
	v_lshlrev_b32_e32 v16, 16, v17
	v_and_b32_e32 v17, 0xffff0000, v17
	v_lshlrev_b32_e32 v34, 16, v20
	v_and_b32_e32 v35, 0xffff0000, v20
	v_lshlrev_b32_e32 v20, 16, v21
	v_and_b32_e32 v21, 0xffff0000, v21
	v_lshlrev_b32_e32 v32, 16, v18
	v_and_b32_e32 v33, 0xffff0000, v18
	v_lshlrev_b32_e32 v18, 16, v19
	v_and_b32_e32 v19, 0xffff0000, v19
	v_lshlrev_b32_e32 v36, 16, v22
	v_and_b32_e32 v37, 0xffff0000, v22
	v_lshlrev_b32_e32 v22, 16, v23
	v_and_b32_e32 v23, 0xffff0000, v23
	v_pk_add_f32 v[30:31], v[30:31], v[34:35]
	v_pk_add_f32 v[16:17], v[16:17], v[20:21]
	v_pk_add_f32 v[20:21], v[32:33], v[36:37]
	v_pk_add_f32 v[18:19], v[18:19], v[22:23]
	v_pk_mul_f32 v[22:23], v[16:17], v[16:17]
	v_pk_mul_f32 v[32:33], v[30:31], v[30:31]
	v_pk_mul_f32 v[34:35], v[18:19], v[18:19]
	v_pk_mul_f32 v[36:37], v[20:21], v[20:21]
	v_pk_mov_b32 v[42:43], v[32:33], v[22:23] op_sel:[1,0]
	v_mov_b32_e32 v33, v23
	v_mov_b32_e32 v22, v34
	v_mov_b32_e32 v23, v36
	v_mov_b32_e32 v36, v35
	v_pk_add_f32 v[32:33], v[42:43], v[32:33]
	v_pk_add_f32 v[22:23], v[22:23], v[36:37]
	v_add_f32_e32 v7, v32, v33
	v_add_f32_e32 v7, v23, v7
	v_add_f32_e32 v7, v22, v7
	ds_bpermute_b32 v22, v0, v7
	v_lshlrev_b32_e32 v38, 16, v24
	v_and_b32_e32 v39, 0xffff0000, v24
	v_lshlrev_b32_e32 v24, 16, v25
	v_and_b32_e32 v25, 0xffff0000, v25
	s_waitcnt lgkmcnt(0)
	v_add_f32_e32 v7, v7, v22
	ds_bpermute_b32 v22, v1, v7
	v_lshlrev_b32_e32 v40, 16, v26
	v_and_b32_e32 v41, 0xffff0000, v26
	v_lshlrev_b32_e32 v26, 16, v27
	v_and_b32_e32 v27, 0xffff0000, v27
	s_waitcnt lgkmcnt(0)
	v_add_f32_e32 v7, v7, v22
	ds_bpermute_b32 v22, v2, v7
	s_waitcnt lgkmcnt(0)
	v_add_f32_e32 v7, v7, v22
	ds_bpermute_b32 v22, v3, v7
	s_waitcnt lgkmcnt(0)
	v_add_f32_e32 v7, v7, v22
	v_fmamk_f32 v7, v7, 0x3c000000, v6
	v_rsq_f32_e32 v22, v7
	s_nop 0
	v_pk_mul_f32 v[16:17], v[16:17], v[22:23] op_sel_hi:[1,0]
	v_pk_mul_f32 v[30:31], v[30:31], v[22:23] op_sel_hi:[1,0]
	v_pk_mul_f32 v[18:19], v[18:19], v[22:23] op_sel_hi:[1,0]
	v_pk_mul_f32 v[20:21], v[20:21], v[22:23] op_sel_hi:[1,0]
	v_pk_mul_f32 v[12:13], v[12:13], v[30:31]
	v_pk_mul_f32 v[14:15], v[14:15], v[16:17]
	v_pk_mul_f32 v[8:9], v[8:9], v[20:21]
	v_pk_mul_f32 v[10:11], v[10:11], v[18:19]
	v_pk_mul_f32 v[14:15], v[14:15], v[24:25]
	v_pk_mul_f32 v[12:13], v[12:13], v[38:39]
	v_pk_mul_f32 v[16:17], v[10:11], v[26:27]
	v_pk_mul_f32 v[10:11], v[8:9], v[40:41]
	v_cvt_pk_bf16_f32 v8, v12, v13
	v_cvt_pk_bf16_f32 v9, v14, v15
	v_cvt_pk_bf16_f32 v10, v10, v11
	v_cvt_pk_bf16_f32 v11, v16, v17
	global_store_dwordx4 v[28:29], v[8:11], off
	s_nop 1
	v_add_u32_e32 v4, 0x10000, v4
	v_ashrrev_i32_e32 v16, 7, v4
	v_ashrrev_i32_e32 v17, 31, v16
	v_and_b32_e32 v7, 0x3f8, v5
	v_lshlrev_b64 v[16:17], 11, v[16:17]
	v_and_b32_e32 v8, 0x78, v5
	v_lshl_or_b32 v16, v7, 1, v16
	v_lshlrev_b32_e32 v12, 2, v8
	v_lshl_add_u64 v[28:29], s[72:73], 0, v[16:17]
	v_lshl_add_u64 v[20:21], s[4:5], 0, v[16:17]
	v_lshl_add_u64 v[24:25], s[88:89], 0, v[16:17]
	global_load_dwordx4 v[8:11], v12, s[18:19] offset:16
	s_nop 0
	global_load_dwordx4 v[12:15], v12, s[18:19]
	s_nop 0
	global_load_dwordx4 v[16:19], v[28:29], off nt
	s_nop 0
	global_load_dwordx4 v[20:23], v[20:21], off nt
	s_nop 0
	global_load_dwordx4 v[24:27], v[24:25], off nt
	v_add_u32_e32 v5, 0x80000, v5
	s_waitcnt vmcnt(6)
	v_lshlrev_b32_e32 v110, 16, v96
	v_and_b32_e32 v111, 0xffff0000, v96
	v_lshlrev_b32_e32 v96, 16, v97
	v_and_b32_e32 v97, 0xffff0000, v97
	v_lshlrev_b32_e32 v114, 16, v100
	v_and_b32_e32 v115, 0xffff0000, v100
	v_lshlrev_b32_e32 v100, 16, v101
	v_and_b32_e32 v101, 0xffff0000, v101
	v_lshlrev_b32_e32 v112, 16, v98
	v_and_b32_e32 v113, 0xffff0000, v98
	v_lshlrev_b32_e32 v98, 16, v99
	v_and_b32_e32 v99, 0xffff0000, v99
	v_lshlrev_b32_e32 v116, 16, v102
	v_and_b32_e32 v117, 0xffff0000, v102
	v_lshlrev_b32_e32 v102, 16, v103
	v_and_b32_e32 v103, 0xffff0000, v103
	v_pk_add_f32 v[110:111], v[110:111], v[114:115]
	v_pk_add_f32 v[96:97], v[96:97], v[100:101]
	v_pk_add_f32 v[100:101], v[112:113], v[116:117]
	v_pk_add_f32 v[98:99], v[98:99], v[102:103]
	v_pk_mul_f32 v[102:103], v[96:97], v[96:97]
	v_pk_mul_f32 v[112:113], v[110:111], v[110:111]
	v_pk_mul_f32 v[114:115], v[98:99], v[98:99]
	v_pk_mul_f32 v[116:117], v[100:101], v[100:101]
	v_pk_mov_b32 v[122:123], v[112:113], v[102:103] op_sel:[1,0]
	v_mov_b32_e32 v113, v103
	v_mov_b32_e32 v102, v114
	v_mov_b32_e32 v103, v116
	v_mov_b32_e32 v116, v115
	v_pk_add_f32 v[112:113], v[122:123], v[112:113]
	v_pk_add_f32 v[102:103], v[102:103], v[116:117]
	v_add_f32_e32 v87, v112, v113
	v_add_f32_e32 v87, v103, v87
	v_add_f32_e32 v87, v102, v87
	ds_bpermute_b32 v102, v0, v87
	v_lshlrev_b32_e32 v118, 16, v104
	v_and_b32_e32 v119, 0xffff0000, v104
	v_lshlrev_b32_e32 v104, 16, v105
	v_and_b32_e32 v105, 0xffff0000, v105
	s_waitcnt lgkmcnt(0)
	v_add_f32_e32 v87, v87, v102
	ds_bpermute_b32 v102, v1, v87
	v_lshlrev_b32_e32 v120, 16, v106
	v_and_b32_e32 v121, 0xffff0000, v106
	v_lshlrev_b32_e32 v106, 16, v107
	v_and_b32_e32 v107, 0xffff0000, v107
	s_waitcnt lgkmcnt(0)
	v_add_f32_e32 v87, v87, v102
	ds_bpermute_b32 v102, v2, v87
	s_waitcnt lgkmcnt(0)
	v_add_f32_e32 v87, v87, v102
	ds_bpermute_b32 v102, v3, v87
	s_waitcnt lgkmcnt(0)
	v_add_f32_e32 v87, v87, v102
	v_fmamk_f32 v87, v87, 0x3c000000, v6
	v_rsq_f32_e32 v102, v87
	s_nop 0
	v_pk_mul_f32 v[96:97], v[96:97], v[102:103] op_sel_hi:[1,0]
	v_pk_mul_f32 v[110:111], v[110:111], v[102:103] op_sel_hi:[1,0]
	v_pk_mul_f32 v[98:99], v[98:99], v[102:103] op_sel_hi:[1,0]
	v_pk_mul_f32 v[100:101], v[100:101], v[102:103] op_sel_hi:[1,0]
	v_pk_mul_f32 v[92:93], v[92:93], v[110:111]
	v_pk_mul_f32 v[94:95], v[94:95], v[96:97]
	v_pk_mul_f32 v[88:89], v[88:89], v[100:101]
	v_pk_mul_f32 v[90:91], v[90:91], v[98:99]
	v_pk_mul_f32 v[94:95], v[94:95], v[104:105]
	v_pk_mul_f32 v[92:93], v[92:93], v[118:119]
	v_pk_mul_f32 v[96:97], v[90:91], v[106:107]
	v_pk_mul_f32 v[90:91], v[88:89], v[120:121]
	v_cvt_pk_bf16_f32 v88, v92, v93
	v_cvt_pk_bf16_f32 v89, v94, v95
	v_cvt_pk_bf16_f32 v90, v90, v91
	v_cvt_pk_bf16_f32 v91, v96, v97
	global_store_dwordx4 v[108:109], v[88:91], off
	s_nop 1
	v_add_u32_e32 v4, 0x10000, v4
	v_ashrrev_i32_e32 v96, 7, v4
	v_ashrrev_i32_e32 v97, 31, v96
	v_and_b32_e32 v87, 0x3f8, v5
	v_lshlrev_b64 v[96:97], 11, v[96:97]
	v_and_b32_e32 v88, 0x78, v5
	v_lshl_or_b32 v96, v87, 1, v96
	v_lshlrev_b32_e32 v92, 2, v88
	v_lshl_add_u64 v[108:109], s[72:73], 0, v[96:97]
	v_lshl_add_u64 v[100:101], s[4:5], 0, v[96:97]
	v_lshl_add_u64 v[104:105], s[88:89], 0, v[96:97]
	global_load_dwordx4 v[88:91], v92, s[18:19] offset:16
	s_nop 0
	global_load_dwordx4 v[92:95], v92, s[18:19]
	s_nop 0
	global_load_dwordx4 v[96:99], v[108:109], off nt
	s_nop 0
	global_load_dwordx4 v[100:103], v[100:101], off nt
	s_nop 0
	global_load_dwordx4 v[104:107], v[104:105], off nt
	v_add_u32_e32 v5, 0x80000, v5
	s_waitcnt vmcnt(6)
	v_lshlrev_b32_e32 v30, 16, v16
	v_and_b32_e32 v31, 0xffff0000, v16
	v_lshlrev_b32_e32 v16, 16, v17
	v_and_b32_e32 v17, 0xffff0000, v17
	v_lshlrev_b32_e32 v34, 16, v20
	v_and_b32_e32 v35, 0xffff0000, v20
	v_lshlrev_b32_e32 v20, 16, v21
	v_and_b32_e32 v21, 0xffff0000, v21
	v_lshlrev_b32_e32 v32, 16, v18
	v_and_b32_e32 v33, 0xffff0000, v18
	v_lshlrev_b32_e32 v18, 16, v19
	v_and_b32_e32 v19, 0xffff0000, v19
	v_lshlrev_b32_e32 v36, 16, v22
	v_and_b32_e32 v37, 0xffff0000, v22
	v_lshlrev_b32_e32 v22, 16, v23
	v_and_b32_e32 v23, 0xffff0000, v23
	v_pk_add_f32 v[30:31], v[30:31], v[34:35]
	v_pk_add_f32 v[16:17], v[16:17], v[20:21]
	v_pk_add_f32 v[20:21], v[32:33], v[36:37]
	v_pk_add_f32 v[18:19], v[18:19], v[22:23]
	v_pk_mul_f32 v[22:23], v[16:17], v[16:17]
	v_pk_mul_f32 v[32:33], v[30:31], v[30:31]
	v_pk_mul_f32 v[34:35], v[18:19], v[18:19]
	v_pk_mul_f32 v[36:37], v[20:21], v[20:21]
	v_pk_mov_b32 v[42:43], v[32:33], v[22:23] op_sel:[1,0]
	v_mov_b32_e32 v33, v23
	v_mov_b32_e32 v22, v34
	v_mov_b32_e32 v23, v36
	v_mov_b32_e32 v36, v35
	v_pk_add_f32 v[32:33], v[42:43], v[32:33]
	v_pk_add_f32 v[22:23], v[22:23], v[36:37]
	v_add_f32_e32 v7, v32, v33
	v_add_f32_e32 v7, v23, v7
	v_add_f32_e32 v7, v22, v7
	ds_bpermute_b32 v22, v0, v7
	v_lshlrev_b32_e32 v38, 16, v24
	v_and_b32_e32 v39, 0xffff0000, v24
	v_lshlrev_b32_e32 v24, 16, v25
	v_and_b32_e32 v25, 0xffff0000, v25
	s_waitcnt lgkmcnt(0)
	v_add_f32_e32 v7, v7, v22
	ds_bpermute_b32 v22, v1, v7
	v_lshlrev_b32_e32 v40, 16, v26
	v_and_b32_e32 v41, 0xffff0000, v26
	v_lshlrev_b32_e32 v26, 16, v27
	v_and_b32_e32 v27, 0xffff0000, v27
	s_waitcnt lgkmcnt(0)
	v_add_f32_e32 v7, v7, v22
	ds_bpermute_b32 v22, v2, v7
	s_waitcnt lgkmcnt(0)
	v_add_f32_e32 v7, v7, v22
	ds_bpermute_b32 v22, v3, v7
	s_waitcnt lgkmcnt(0)
	v_add_f32_e32 v7, v7, v22
	v_fmamk_f32 v7, v7, 0x3c000000, v6
	v_rsq_f32_e32 v22, v7
	s_nop 0
	v_pk_mul_f32 v[16:17], v[16:17], v[22:23] op_sel_hi:[1,0]
	v_pk_mul_f32 v[30:31], v[30:31], v[22:23] op_sel_hi:[1,0]
	v_pk_mul_f32 v[18:19], v[18:19], v[22:23] op_sel_hi:[1,0]
	v_pk_mul_f32 v[20:21], v[20:21], v[22:23] op_sel_hi:[1,0]
	v_pk_mul_f32 v[12:13], v[12:13], v[30:31]
	v_pk_mul_f32 v[14:15], v[14:15], v[16:17]
	v_pk_mul_f32 v[8:9], v[8:9], v[20:21]
	v_pk_mul_f32 v[10:11], v[10:11], v[18:19]
	v_pk_mul_f32 v[14:15], v[14:15], v[24:25]
	v_pk_mul_f32 v[12:13], v[12:13], v[38:39]
	v_pk_mul_f32 v[16:17], v[10:11], v[26:27]
	v_pk_mul_f32 v[10:11], v[8:9], v[40:41]
	v_cvt_pk_bf16_f32 v8, v12, v13
	v_cvt_pk_bf16_f32 v9, v14, v15
	v_cvt_pk_bf16_f32 v10, v10, v11
	v_cvt_pk_bf16_f32 v11, v16, v17
	global_store_dwordx4 v[28:29], v[8:11], off
	s_nop 1
	v_add_u32_e32 v4, 0x10000, v4
	v_ashrrev_i32_e32 v16, 7, v4
	v_ashrrev_i32_e32 v17, 31, v16
	v_and_b32_e32 v7, 0x3f8, v5
	v_lshlrev_b64 v[16:17], 11, v[16:17]
	v_and_b32_e32 v8, 0x78, v5
	v_lshl_or_b32 v16, v7, 1, v16
	v_lshlrev_b32_e32 v12, 2, v8
	v_lshl_add_u64 v[28:29], s[72:73], 0, v[16:17]
	v_lshl_add_u64 v[20:21], s[4:5], 0, v[16:17]
	v_lshl_add_u64 v[24:25], s[88:89], 0, v[16:17]
	global_load_dwordx4 v[8:11], v12, s[18:19] offset:16
	s_nop 0
	global_load_dwordx4 v[12:15], v12, s[18:19]
	s_nop 0
	global_load_dwordx4 v[16:19], v[28:29], off nt
	s_nop 0
	global_load_dwordx4 v[20:23], v[20:21], off nt
	s_nop 0
	global_load_dwordx4 v[24:27], v[24:25], off nt
	v_add_u32_e32 v5, 0x80000, v5
	s_waitcnt vmcnt(6)
	v_lshlrev_b32_e32 v110, 16, v96
	v_and_b32_e32 v111, 0xffff0000, v96
	v_lshlrev_b32_e32 v96, 16, v97
	v_and_b32_e32 v97, 0xffff0000, v97
	v_lshlrev_b32_e32 v114, 16, v100
	v_and_b32_e32 v115, 0xffff0000, v100
	v_lshlrev_b32_e32 v100, 16, v101
	v_and_b32_e32 v101, 0xffff0000, v101
	v_lshlrev_b32_e32 v112, 16, v98
	v_and_b32_e32 v113, 0xffff0000, v98
	v_lshlrev_b32_e32 v98, 16, v99
	v_and_b32_e32 v99, 0xffff0000, v99
	v_lshlrev_b32_e32 v116, 16, v102
	v_and_b32_e32 v117, 0xffff0000, v102
	v_lshlrev_b32_e32 v102, 16, v103
	v_and_b32_e32 v103, 0xffff0000, v103
	v_pk_add_f32 v[110:111], v[110:111], v[114:115]
	v_pk_add_f32 v[96:97], v[96:97], v[100:101]
	v_pk_add_f32 v[100:101], v[112:113], v[116:117]
	v_pk_add_f32 v[98:99], v[98:99], v[102:103]
	v_pk_mul_f32 v[102:103], v[96:97], v[96:97]
	v_pk_mul_f32 v[112:113], v[110:111], v[110:111]
	v_pk_mul_f32 v[114:115], v[98:99], v[98:99]
	v_pk_mul_f32 v[116:117], v[100:101], v[100:101]
	v_pk_mov_b32 v[122:123], v[112:113], v[102:103] op_sel:[1,0]
	v_mov_b32_e32 v113, v103
	v_mov_b32_e32 v102, v114
	v_mov_b32_e32 v103, v116
	v_mov_b32_e32 v116, v115
	v_pk_add_f32 v[112:113], v[122:123], v[112:113]
	v_pk_add_f32 v[102:103], v[102:103], v[116:117]
	v_add_f32_e32 v87, v112, v113
	v_add_f32_e32 v87, v103, v87
	v_add_f32_e32 v87, v102, v87
	ds_bpermute_b32 v102, v0, v87
	v_lshlrev_b32_e32 v118, 16, v104
	v_and_b32_e32 v119, 0xffff0000, v104
	v_lshlrev_b32_e32 v104, 16, v105
	v_and_b32_e32 v105, 0xffff0000, v105
	s_waitcnt lgkmcnt(0)
	v_add_f32_e32 v87, v87, v102
	ds_bpermute_b32 v102, v1, v87
	v_lshlrev_b32_e32 v120, 16, v106
	v_and_b32_e32 v121, 0xffff0000, v106
	v_lshlrev_b32_e32 v106, 16, v107
	v_and_b32_e32 v107, 0xffff0000, v107
	s_waitcnt lgkmcnt(0)
	v_add_f32_e32 v87, v87, v102
	ds_bpermute_b32 v102, v2, v87
	s_waitcnt lgkmcnt(0)
	v_add_f32_e32 v87, v87, v102
	ds_bpermute_b32 v102, v3, v87
	s_waitcnt lgkmcnt(0)
	v_add_f32_e32 v87, v87, v102
	v_fmamk_f32 v87, v87, 0x3c000000, v6
	v_rsq_f32_e32 v102, v87
	s_nop 0
	v_pk_mul_f32 v[96:97], v[96:97], v[102:103] op_sel_hi:[1,0]
	v_pk_mul_f32 v[110:111], v[110:111], v[102:103] op_sel_hi:[1,0]
	v_pk_mul_f32 v[98:99], v[98:99], v[102:103] op_sel_hi:[1,0]
	v_pk_mul_f32 v[100:101], v[100:101], v[102:103] op_sel_hi:[1,0]
	v_pk_mul_f32 v[92:93], v[92:93], v[110:111]
	v_pk_mul_f32 v[94:95], v[94:95], v[96:97]
	v_pk_mul_f32 v[88:89], v[88:89], v[100:101]
	v_pk_mul_f32 v[90:91], v[90:91], v[98:99]
	v_pk_mul_f32 v[94:95], v[94:95], v[104:105]
	v_pk_mul_f32 v[92:93], v[92:93], v[118:119]
	v_pk_mul_f32 v[96:97], v[90:91], v[106:107]
	v_pk_mul_f32 v[90:91], v[88:89], v[120:121]
	v_cvt_pk_bf16_f32 v88, v92, v93
	v_cvt_pk_bf16_f32 v89, v94, v95
	v_cvt_pk_bf16_f32 v90, v90, v91
	v_cvt_pk_bf16_f32 v91, v96, v97
	global_store_dwordx4 v[108:109], v[88:91], off
	s_nop 1
	v_add_u32_e32 v4, 0x10000, v4
	v_ashrrev_i32_e32 v96, 7, v4
	v_ashrrev_i32_e32 v97, 31, v96
	v_and_b32_e32 v87, 0x3f8, v5
	v_lshlrev_b64 v[96:97], 11, v[96:97]
	v_and_b32_e32 v88, 0x78, v5
	v_lshl_or_b32 v96, v87, 1, v96
	v_lshlrev_b32_e32 v92, 2, v88
	v_lshl_add_u64 v[108:109], s[72:73], 0, v[96:97]
	v_lshl_add_u64 v[100:101], s[4:5], 0, v[96:97]
	v_lshl_add_u64 v[104:105], s[88:89], 0, v[96:97]
	global_load_dwordx4 v[88:91], v92, s[18:19] offset:16
	s_nop 0
	global_load_dwordx4 v[92:95], v92, s[18:19]
	s_nop 0
	global_load_dwordx4 v[96:99], v[108:109], off nt
	s_nop 0
	global_load_dwordx4 v[100:103], v[100:101], off nt
	s_nop 0
	global_load_dwordx4 v[104:107], v[104:105], off nt
	v_add_u32_e32 v5, 0x80000, v5
	s_waitcnt vmcnt(6)
	v_lshlrev_b32_e32 v30, 16, v16
	v_and_b32_e32 v31, 0xffff0000, v16
	v_lshlrev_b32_e32 v16, 16, v17
	v_and_b32_e32 v17, 0xffff0000, v17
	v_lshlrev_b32_e32 v34, 16, v20
	v_and_b32_e32 v35, 0xffff0000, v20
	v_lshlrev_b32_e32 v20, 16, v21
	v_and_b32_e32 v21, 0xffff0000, v21
	v_lshlrev_b32_e32 v32, 16, v18
	v_and_b32_e32 v33, 0xffff0000, v18
	v_lshlrev_b32_e32 v18, 16, v19
	v_and_b32_e32 v19, 0xffff0000, v19
	v_lshlrev_b32_e32 v36, 16, v22
	v_and_b32_e32 v37, 0xffff0000, v22
	v_lshlrev_b32_e32 v22, 16, v23
	v_and_b32_e32 v23, 0xffff0000, v23
	v_pk_add_f32 v[30:31], v[30:31], v[34:35]
	v_pk_add_f32 v[16:17], v[16:17], v[20:21]
	v_pk_add_f32 v[20:21], v[32:33], v[36:37]
	v_pk_add_f32 v[18:19], v[18:19], v[22:23]
	v_pk_mul_f32 v[22:23], v[16:17], v[16:17]
	v_pk_mul_f32 v[32:33], v[30:31], v[30:31]
	v_pk_mul_f32 v[34:35], v[18:19], v[18:19]
	v_pk_mul_f32 v[36:37], v[20:21], v[20:21]
	v_pk_mov_b32 v[42:43], v[32:33], v[22:23] op_sel:[1,0]
	v_mov_b32_e32 v33, v23
	v_mov_b32_e32 v22, v34
	v_mov_b32_e32 v23, v36
	v_mov_b32_e32 v36, v35
	v_pk_add_f32 v[32:33], v[42:43], v[32:33]
	v_pk_add_f32 v[22:23], v[22:23], v[36:37]
	v_add_f32_e32 v7, v32, v33
	v_add_f32_e32 v7, v23, v7
	v_add_f32_e32 v7, v22, v7
	ds_bpermute_b32 v22, v0, v7
	v_lshlrev_b32_e32 v38, 16, v24
	v_and_b32_e32 v39, 0xffff0000, v24
	v_lshlrev_b32_e32 v24, 16, v25
	v_and_b32_e32 v25, 0xffff0000, v25
	s_waitcnt lgkmcnt(0)
	v_add_f32_e32 v7, v7, v22
	ds_bpermute_b32 v22, v1, v7
	v_lshlrev_b32_e32 v40, 16, v26
	v_and_b32_e32 v41, 0xffff0000, v26
	v_lshlrev_b32_e32 v26, 16, v27
	v_and_b32_e32 v27, 0xffff0000, v27
	s_waitcnt lgkmcnt(0)
	v_add_f32_e32 v7, v7, v22
	ds_bpermute_b32 v22, v2, v7
	s_waitcnt lgkmcnt(0)
	v_add_f32_e32 v7, v7, v22
	ds_bpermute_b32 v22, v3, v7
	s_waitcnt lgkmcnt(0)
	v_add_f32_e32 v7, v7, v22
	v_fmamk_f32 v7, v7, 0x3c000000, v6
	v_rsq_f32_e32 v22, v7
	s_nop 0
	v_pk_mul_f32 v[16:17], v[16:17], v[22:23] op_sel_hi:[1,0]
	v_pk_mul_f32 v[30:31], v[30:31], v[22:23] op_sel_hi:[1,0]
	v_pk_mul_f32 v[18:19], v[18:19], v[22:23] op_sel_hi:[1,0]
	v_pk_mul_f32 v[20:21], v[20:21], v[22:23] op_sel_hi:[1,0]
	v_pk_mul_f32 v[12:13], v[12:13], v[30:31]
	v_pk_mul_f32 v[14:15], v[14:15], v[16:17]
	v_pk_mul_f32 v[8:9], v[8:9], v[20:21]
	v_pk_mul_f32 v[10:11], v[10:11], v[18:19]
	v_pk_mul_f32 v[14:15], v[14:15], v[24:25]
	v_pk_mul_f32 v[12:13], v[12:13], v[38:39]
	v_pk_mul_f32 v[16:17], v[10:11], v[26:27]
	v_pk_mul_f32 v[10:11], v[8:9], v[40:41]
	v_cvt_pk_bf16_f32 v8, v12, v13
	v_cvt_pk_bf16_f32 v9, v14, v15
	v_cvt_pk_bf16_f32 v10, v10, v11
	v_cvt_pk_bf16_f32 v11, v16, v17
	global_store_dwordx4 v[28:29], v[8:11], off
	s_nop 1
	v_add_u32_e32 v4, 0x10000, v4
	v_ashrrev_i32_e32 v16, 7, v4
	v_ashrrev_i32_e32 v17, 31, v16
	v_and_b32_e32 v7, 0x3f8, v5
	v_lshlrev_b64 v[16:17], 11, v[16:17]
	v_and_b32_e32 v8, 0x78, v5
	v_lshl_or_b32 v16, v7, 1, v16
	v_lshlrev_b32_e32 v12, 2, v8
	v_lshl_add_u64 v[28:29], s[72:73], 0, v[16:17]
	v_lshl_add_u64 v[20:21], s[4:5], 0, v[16:17]
	v_lshl_add_u64 v[24:25], s[88:89], 0, v[16:17]
	global_load_dwordx4 v[8:11], v12, s[18:19] offset:16
	s_nop 0
	global_load_dwordx4 v[12:15], v12, s[18:19]
	s_nop 0
	global_load_dwordx4 v[16:19], v[28:29], off nt
	s_nop 0
	global_load_dwordx4 v[20:23], v[20:21], off nt
	s_nop 0
	global_load_dwordx4 v[24:27], v[24:25], off nt
	v_add_u32_e32 v5, 0x80000, v5
	s_waitcnt vmcnt(6)
	v_lshlrev_b32_e32 v110, 16, v96
	v_and_b32_e32 v111, 0xffff0000, v96
	v_lshlrev_b32_e32 v96, 16, v97
	v_and_b32_e32 v97, 0xffff0000, v97
	v_lshlrev_b32_e32 v114, 16, v100
	v_and_b32_e32 v115, 0xffff0000, v100
	v_lshlrev_b32_e32 v100, 16, v101
	v_and_b32_e32 v101, 0xffff0000, v101
	v_lshlrev_b32_e32 v112, 16, v98
	v_and_b32_e32 v113, 0xffff0000, v98
	v_lshlrev_b32_e32 v98, 16, v99
	v_and_b32_e32 v99, 0xffff0000, v99
	v_lshlrev_b32_e32 v116, 16, v102
	v_and_b32_e32 v117, 0xffff0000, v102
	v_lshlrev_b32_e32 v102, 16, v103
	v_and_b32_e32 v103, 0xffff0000, v103
	v_pk_add_f32 v[110:111], v[110:111], v[114:115]
	v_pk_add_f32 v[96:97], v[96:97], v[100:101]
	v_pk_add_f32 v[100:101], v[112:113], v[116:117]
	v_pk_add_f32 v[98:99], v[98:99], v[102:103]
	v_pk_mul_f32 v[102:103], v[96:97], v[96:97]
	v_pk_mul_f32 v[112:113], v[110:111], v[110:111]
	v_pk_mul_f32 v[114:115], v[98:99], v[98:99]
	v_pk_mul_f32 v[116:117], v[100:101], v[100:101]
	v_pk_mov_b32 v[122:123], v[112:113], v[102:103] op_sel:[1,0]
	v_mov_b32_e32 v113, v103
	v_mov_b32_e32 v102, v114
	v_mov_b32_e32 v103, v116
	v_mov_b32_e32 v116, v115
	v_pk_add_f32 v[112:113], v[122:123], v[112:113]
	v_pk_add_f32 v[102:103], v[102:103], v[116:117]
	v_add_f32_e32 v87, v112, v113
	v_add_f32_e32 v87, v103, v87
	v_add_f32_e32 v87, v102, v87
	ds_bpermute_b32 v102, v0, v87
	v_lshlrev_b32_e32 v118, 16, v104
	v_and_b32_e32 v119, 0xffff0000, v104
	v_lshlrev_b32_e32 v104, 16, v105
	v_and_b32_e32 v105, 0xffff0000, v105
	s_waitcnt lgkmcnt(0)
	v_add_f32_e32 v87, v87, v102
	ds_bpermute_b32 v102, v1, v87
	v_lshlrev_b32_e32 v120, 16, v106
	v_and_b32_e32 v121, 0xffff0000, v106
	v_lshlrev_b32_e32 v106, 16, v107
	v_and_b32_e32 v107, 0xffff0000, v107
	s_waitcnt lgkmcnt(0)
	v_add_f32_e32 v87, v87, v102
	ds_bpermute_b32 v102, v2, v87
	s_waitcnt lgkmcnt(0)
	v_add_f32_e32 v87, v87, v102
	ds_bpermute_b32 v102, v3, v87
	s_waitcnt lgkmcnt(0)
	v_add_f32_e32 v87, v87, v102
	v_fmamk_f32 v87, v87, 0x3c000000, v6
	v_rsq_f32_e32 v102, v87
	s_nop 0
	v_pk_mul_f32 v[96:97], v[96:97], v[102:103] op_sel_hi:[1,0]
	v_pk_mul_f32 v[110:111], v[110:111], v[102:103] op_sel_hi:[1,0]
	v_pk_mul_f32 v[98:99], v[98:99], v[102:103] op_sel_hi:[1,0]
	v_pk_mul_f32 v[100:101], v[100:101], v[102:103] op_sel_hi:[1,0]
	v_pk_mul_f32 v[92:93], v[92:93], v[110:111]
	v_pk_mul_f32 v[94:95], v[94:95], v[96:97]
	v_pk_mul_f32 v[88:89], v[88:89], v[100:101]
	v_pk_mul_f32 v[90:91], v[90:91], v[98:99]
	v_pk_mul_f32 v[94:95], v[94:95], v[104:105]
	v_pk_mul_f32 v[92:93], v[92:93], v[118:119]
	v_pk_mul_f32 v[96:97], v[90:91], v[106:107]
	v_pk_mul_f32 v[90:91], v[88:89], v[120:121]
	v_cvt_pk_bf16_f32 v88, v92, v93
	v_cvt_pk_bf16_f32 v89, v94, v95
	v_cvt_pk_bf16_f32 v90, v90, v91
	v_cvt_pk_bf16_f32 v91, v96, v97
	global_store_dwordx4 v[108:109], v[88:91], off
	s_nop 1
	v_add_u32_e32 v4, 0x10000, v4
	v_ashrrev_i32_e32 v96, 7, v4
	v_ashrrev_i32_e32 v97, 31, v96
	v_and_b32_e32 v87, 0x3f8, v5
	v_lshlrev_b64 v[96:97], 11, v[96:97]
	v_and_b32_e32 v88, 0x78, v5
	v_lshl_or_b32 v96, v87, 1, v96
	v_lshlrev_b32_e32 v92, 2, v88
	v_lshl_add_u64 v[108:109], s[72:73], 0, v[96:97]
	v_lshl_add_u64 v[100:101], s[4:5], 0, v[96:97]
	v_lshl_add_u64 v[104:105], s[88:89], 0, v[96:97]
	global_load_dwordx4 v[88:91], v92, s[18:19] offset:16
	s_nop 0
	global_load_dwordx4 v[92:95], v92, s[18:19]
	s_nop 0
	global_load_dwordx4 v[96:99], v[108:109], off nt
	s_nop 0
	global_load_dwordx4 v[100:103], v[100:101], off nt
	s_nop 0
	global_load_dwordx4 v[104:107], v[104:105], off nt
	v_add_u32_e32 v5, 0x80000, v5
	s_waitcnt vmcnt(6)
	v_lshlrev_b32_e32 v30, 16, v16
	v_and_b32_e32 v31, 0xffff0000, v16
	v_lshlrev_b32_e32 v16, 16, v17
	v_and_b32_e32 v17, 0xffff0000, v17
	v_lshlrev_b32_e32 v34, 16, v20
	v_and_b32_e32 v35, 0xffff0000, v20
	v_lshlrev_b32_e32 v20, 16, v21
	v_and_b32_e32 v21, 0xffff0000, v21
	v_lshlrev_b32_e32 v32, 16, v18
	v_and_b32_e32 v33, 0xffff0000, v18
	v_lshlrev_b32_e32 v18, 16, v19
	v_and_b32_e32 v19, 0xffff0000, v19
	v_lshlrev_b32_e32 v36, 16, v22
	v_and_b32_e32 v37, 0xffff0000, v22
	v_lshlrev_b32_e32 v22, 16, v23
	v_and_b32_e32 v23, 0xffff0000, v23
	v_pk_add_f32 v[30:31], v[30:31], v[34:35]
	v_pk_add_f32 v[16:17], v[16:17], v[20:21]
	v_pk_add_f32 v[20:21], v[32:33], v[36:37]
	v_pk_add_f32 v[18:19], v[18:19], v[22:23]
	v_pk_mul_f32 v[22:23], v[16:17], v[16:17]
	v_pk_mul_f32 v[32:33], v[30:31], v[30:31]
	v_pk_mul_f32 v[34:35], v[18:19], v[18:19]
	v_pk_mul_f32 v[36:37], v[20:21], v[20:21]
	v_pk_mov_b32 v[42:43], v[32:33], v[22:23] op_sel:[1,0]
	v_mov_b32_e32 v33, v23
	v_mov_b32_e32 v22, v34
	v_mov_b32_e32 v23, v36
	v_mov_b32_e32 v36, v35
	v_pk_add_f32 v[32:33], v[42:43], v[32:33]
	v_pk_add_f32 v[22:23], v[22:23], v[36:37]
	v_add_f32_e32 v7, v32, v33
	v_add_f32_e32 v7, v23, v7
	v_add_f32_e32 v7, v22, v7
	ds_bpermute_b32 v22, v0, v7
	v_lshlrev_b32_e32 v38, 16, v24
	v_and_b32_e32 v39, 0xffff0000, v24
	v_lshlrev_b32_e32 v24, 16, v25
	v_and_b32_e32 v25, 0xffff0000, v25
	s_waitcnt lgkmcnt(0)
	v_add_f32_e32 v7, v7, v22
	ds_bpermute_b32 v22, v1, v7
	v_lshlrev_b32_e32 v40, 16, v26
	v_and_b32_e32 v41, 0xffff0000, v26
	v_lshlrev_b32_e32 v26, 16, v27
	v_and_b32_e32 v27, 0xffff0000, v27
	s_waitcnt lgkmcnt(0)
	v_add_f32_e32 v7, v7, v22
	ds_bpermute_b32 v22, v2, v7
	s_waitcnt lgkmcnt(0)
	v_add_f32_e32 v7, v7, v22
	ds_bpermute_b32 v22, v3, v7
	s_waitcnt lgkmcnt(0)
	v_add_f32_e32 v7, v7, v22
	v_fmamk_f32 v7, v7, 0x3c000000, v6
	v_rsq_f32_e32 v22, v7
	s_nop 0
	v_pk_mul_f32 v[16:17], v[16:17], v[22:23] op_sel_hi:[1,0]
	v_pk_mul_f32 v[30:31], v[30:31], v[22:23] op_sel_hi:[1,0]
	v_pk_mul_f32 v[18:19], v[18:19], v[22:23] op_sel_hi:[1,0]
	v_pk_mul_f32 v[20:21], v[20:21], v[22:23] op_sel_hi:[1,0]
	v_pk_mul_f32 v[12:13], v[12:13], v[30:31]
	v_pk_mul_f32 v[14:15], v[14:15], v[16:17]
	v_pk_mul_f32 v[8:9], v[8:9], v[20:21]
	v_pk_mul_f32 v[10:11], v[10:11], v[18:19]
	v_pk_mul_f32 v[14:15], v[14:15], v[24:25]
	v_pk_mul_f32 v[12:13], v[12:13], v[38:39]
	v_pk_mul_f32 v[16:17], v[10:11], v[26:27]
	v_pk_mul_f32 v[10:11], v[8:9], v[40:41]
	v_cvt_pk_bf16_f32 v8, v12, v13
	v_cvt_pk_bf16_f32 v9, v14, v15
	v_cvt_pk_bf16_f32 v10, v10, v11
	v_cvt_pk_bf16_f32 v11, v16, v17
	global_store_dwordx4 v[28:29], v[8:11], off
	s_nop 1
	v_add_u32_e32 v4, 0x10000, v4
	v_ashrrev_i32_e32 v16, 7, v4
	v_ashrrev_i32_e32 v17, 31, v16
	v_and_b32_e32 v7, 0x3f8, v5
	v_lshlrev_b64 v[16:17], 11, v[16:17]
	v_and_b32_e32 v8, 0x78, v5
	v_lshl_or_b32 v16, v7, 1, v16
	v_lshlrev_b32_e32 v12, 2, v8
	v_lshl_add_u64 v[28:29], s[72:73], 0, v[16:17]
	v_lshl_add_u64 v[20:21], s[4:5], 0, v[16:17]
	v_lshl_add_u64 v[24:25], s[88:89], 0, v[16:17]
	global_load_dwordx4 v[8:11], v12, s[18:19] offset:16
	s_nop 0
	global_load_dwordx4 v[12:15], v12, s[18:19]
	s_nop 0
	global_load_dwordx4 v[16:19], v[28:29], off nt
	s_nop 0
	global_load_dwordx4 v[20:23], v[20:21], off nt
	s_nop 0
	global_load_dwordx4 v[24:27], v[24:25], off nt
	v_add_u32_e32 v5, 0x80000, v5
	s_waitcnt vmcnt(6)
	v_lshlrev_b32_e32 v110, 16, v96
	v_and_b32_e32 v111, 0xffff0000, v96
	v_lshlrev_b32_e32 v96, 16, v97
	v_and_b32_e32 v97, 0xffff0000, v97
	v_lshlrev_b32_e32 v114, 16, v100
	v_and_b32_e32 v115, 0xffff0000, v100
	v_lshlrev_b32_e32 v100, 16, v101
	v_and_b32_e32 v101, 0xffff0000, v101
	v_lshlrev_b32_e32 v112, 16, v98
	v_and_b32_e32 v113, 0xffff0000, v98
	v_lshlrev_b32_e32 v98, 16, v99
	v_and_b32_e32 v99, 0xffff0000, v99
	v_lshlrev_b32_e32 v116, 16, v102
	v_and_b32_e32 v117, 0xffff0000, v102
	v_lshlrev_b32_e32 v102, 16, v103
	v_and_b32_e32 v103, 0xffff0000, v103
	v_pk_add_f32 v[110:111], v[110:111], v[114:115]
	v_pk_add_f32 v[96:97], v[96:97], v[100:101]
	v_pk_add_f32 v[100:101], v[112:113], v[116:117]
	v_pk_add_f32 v[98:99], v[98:99], v[102:103]
	v_pk_mul_f32 v[102:103], v[96:97], v[96:97]
	v_pk_mul_f32 v[112:113], v[110:111], v[110:111]
	v_pk_mul_f32 v[114:115], v[98:99], v[98:99]
	v_pk_mul_f32 v[116:117], v[100:101], v[100:101]
	v_pk_mov_b32 v[122:123], v[112:113], v[102:103] op_sel:[1,0]
	v_mov_b32_e32 v113, v103
	v_mov_b32_e32 v102, v114
	v_mov_b32_e32 v103, v116
	v_mov_b32_e32 v116, v115
	v_pk_add_f32 v[112:113], v[122:123], v[112:113]
	v_pk_add_f32 v[102:103], v[102:103], v[116:117]
	v_add_f32_e32 v87, v112, v113
	v_add_f32_e32 v87, v103, v87
	v_add_f32_e32 v87, v102, v87
	ds_bpermute_b32 v102, v0, v87
	v_lshlrev_b32_e32 v118, 16, v104
	v_and_b32_e32 v119, 0xffff0000, v104
	v_lshlrev_b32_e32 v104, 16, v105
	v_and_b32_e32 v105, 0xffff0000, v105
	s_waitcnt lgkmcnt(0)
	v_add_f32_e32 v87, v87, v102
	ds_bpermute_b32 v102, v1, v87
	v_lshlrev_b32_e32 v120, 16, v106
	v_and_b32_e32 v121, 0xffff0000, v106
	v_lshlrev_b32_e32 v106, 16, v107
	v_and_b32_e32 v107, 0xffff0000, v107
	s_waitcnt lgkmcnt(0)
	v_add_f32_e32 v87, v87, v102
	ds_bpermute_b32 v102, v2, v87
	s_waitcnt lgkmcnt(0)
	v_add_f32_e32 v87, v87, v102
	ds_bpermute_b32 v102, v3, v87
	s_waitcnt lgkmcnt(0)
	v_add_f32_e32 v87, v87, v102
	v_fmamk_f32 v87, v87, 0x3c000000, v6
	v_rsq_f32_e32 v102, v87
	s_nop 0
	v_pk_mul_f32 v[96:97], v[96:97], v[102:103] op_sel_hi:[1,0]
	v_pk_mul_f32 v[110:111], v[110:111], v[102:103] op_sel_hi:[1,0]
	v_pk_mul_f32 v[98:99], v[98:99], v[102:103] op_sel_hi:[1,0]
	v_pk_mul_f32 v[100:101], v[100:101], v[102:103] op_sel_hi:[1,0]
	v_pk_mul_f32 v[92:93], v[92:93], v[110:111]
	v_pk_mul_f32 v[94:95], v[94:95], v[96:97]
	v_pk_mul_f32 v[88:89], v[88:89], v[100:101]
	v_pk_mul_f32 v[90:91], v[90:91], v[98:99]
	v_pk_mul_f32 v[94:95], v[94:95], v[104:105]
	v_pk_mul_f32 v[92:93], v[92:93], v[118:119]
	v_pk_mul_f32 v[96:97], v[90:91], v[106:107]
	v_pk_mul_f32 v[90:91], v[88:89], v[120:121]
	v_cvt_pk_bf16_f32 v88, v92, v93
	v_cvt_pk_bf16_f32 v89, v94, v95
	v_cvt_pk_bf16_f32 v90, v90, v91
	v_cvt_pk_bf16_f32 v91, v96, v97
	global_store_dwordx4 v[108:109], v[88:91], off
	s_nop 1
	v_add_u32_e32 v4, 0x10000, v4
	v_ashrrev_i32_e32 v96, 7, v4
	v_ashrrev_i32_e32 v97, 31, v96
	v_and_b32_e32 v87, 0x3f8, v5
	v_lshlrev_b64 v[96:97], 11, v[96:97]
	v_and_b32_e32 v88, 0x78, v5
	v_lshl_or_b32 v96, v87, 1, v96
	v_lshlrev_b32_e32 v92, 2, v88
	v_lshl_add_u64 v[108:109], s[72:73], 0, v[96:97]
	v_lshl_add_u64 v[100:101], s[4:5], 0, v[96:97]
	v_lshl_add_u64 v[104:105], s[88:89], 0, v[96:97]
	global_load_dwordx4 v[88:91], v92, s[18:19] offset:16
	s_nop 0
	global_load_dwordx4 v[92:95], v92, s[18:19]
	s_nop 0
	global_load_dwordx4 v[96:99], v[108:109], off nt
	s_nop 0
	global_load_dwordx4 v[100:103], v[100:101], off nt
	s_nop 0
	global_load_dwordx4 v[104:107], v[104:105], off nt
	v_add_u32_e32 v5, 0x80000, v5
	s_waitcnt vmcnt(6)
	v_lshlrev_b32_e32 v30, 16, v16
	v_and_b32_e32 v31, 0xffff0000, v16
	v_lshlrev_b32_e32 v16, 16, v17
	v_and_b32_e32 v17, 0xffff0000, v17
	v_lshlrev_b32_e32 v34, 16, v20
	v_and_b32_e32 v35, 0xffff0000, v20
	v_lshlrev_b32_e32 v20, 16, v21
	v_and_b32_e32 v21, 0xffff0000, v21
	v_lshlrev_b32_e32 v32, 16, v18
	v_and_b32_e32 v33, 0xffff0000, v18
	v_lshlrev_b32_e32 v18, 16, v19
	v_and_b32_e32 v19, 0xffff0000, v19
	v_lshlrev_b32_e32 v36, 16, v22
	v_and_b32_e32 v37, 0xffff0000, v22
	v_lshlrev_b32_e32 v22, 16, v23
	v_and_b32_e32 v23, 0xffff0000, v23
	v_pk_add_f32 v[30:31], v[30:31], v[34:35]
	v_pk_add_f32 v[16:17], v[16:17], v[20:21]
	v_pk_add_f32 v[20:21], v[32:33], v[36:37]
	v_pk_add_f32 v[18:19], v[18:19], v[22:23]
	v_pk_mul_f32 v[22:23], v[16:17], v[16:17]
	v_pk_mul_f32 v[32:33], v[30:31], v[30:31]
	v_pk_mul_f32 v[34:35], v[18:19], v[18:19]
	v_pk_mul_f32 v[36:37], v[20:21], v[20:21]
	v_pk_mov_b32 v[42:43], v[32:33], v[22:23] op_sel:[1,0]
	v_mov_b32_e32 v33, v23
	v_mov_b32_e32 v22, v34
	v_mov_b32_e32 v23, v36
	v_mov_b32_e32 v36, v35
	v_pk_add_f32 v[32:33], v[42:43], v[32:33]
	v_pk_add_f32 v[22:23], v[22:23], v[36:37]
	v_add_f32_e32 v7, v32, v33
	v_add_f32_e32 v7, v23, v7
	v_add_f32_e32 v7, v22, v7
	ds_bpermute_b32 v22, v0, v7
	v_lshlrev_b32_e32 v38, 16, v24
	v_and_b32_e32 v39, 0xffff0000, v24
	v_lshlrev_b32_e32 v24, 16, v25
	v_and_b32_e32 v25, 0xffff0000, v25
	s_waitcnt lgkmcnt(0)
	v_add_f32_e32 v7, v7, v22
	ds_bpermute_b32 v22, v1, v7
	v_lshlrev_b32_e32 v40, 16, v26
	v_and_b32_e32 v41, 0xffff0000, v26
	v_lshlrev_b32_e32 v26, 16, v27
	v_and_b32_e32 v27, 0xffff0000, v27
	s_waitcnt lgkmcnt(0)
	v_add_f32_e32 v7, v7, v22
	ds_bpermute_b32 v22, v2, v7
	s_waitcnt lgkmcnt(0)
	v_add_f32_e32 v7, v7, v22
	ds_bpermute_b32 v22, v3, v7
	s_waitcnt lgkmcnt(0)
	v_add_f32_e32 v7, v7, v22
	v_fmamk_f32 v7, v7, 0x3c000000, v6
	v_rsq_f32_e32 v22, v7
	s_nop 0
	v_pk_mul_f32 v[16:17], v[16:17], v[22:23] op_sel_hi:[1,0]
	v_pk_mul_f32 v[30:31], v[30:31], v[22:23] op_sel_hi:[1,0]
	v_pk_mul_f32 v[18:19], v[18:19], v[22:23] op_sel_hi:[1,0]
	v_pk_mul_f32 v[20:21], v[20:21], v[22:23] op_sel_hi:[1,0]
	v_pk_mul_f32 v[12:13], v[12:13], v[30:31]
	v_pk_mul_f32 v[14:15], v[14:15], v[16:17]
	v_pk_mul_f32 v[8:9], v[8:9], v[20:21]
	v_pk_mul_f32 v[10:11], v[10:11], v[18:19]
	v_pk_mul_f32 v[14:15], v[14:15], v[24:25]
	v_pk_mul_f32 v[12:13], v[12:13], v[38:39]
	v_pk_mul_f32 v[16:17], v[10:11], v[26:27]
	v_pk_mul_f32 v[10:11], v[8:9], v[40:41]
	v_cvt_pk_bf16_f32 v8, v12, v13
	v_cvt_pk_bf16_f32 v9, v14, v15
	v_cvt_pk_bf16_f32 v10, v10, v11
	v_cvt_pk_bf16_f32 v11, v16, v17
	global_store_dwordx4 v[28:29], v[8:11], off
	s_nop 1
	v_add_u32_e32 v4, 0x10000, v4
	v_ashrrev_i32_e32 v16, 7, v4
	v_ashrrev_i32_e32 v17, 31, v16
	v_and_b32_e32 v7, 0x3f8, v5
	v_lshlrev_b64 v[16:17], 11, v[16:17]
	v_and_b32_e32 v8, 0x78, v5
	v_lshl_or_b32 v16, v7, 1, v16
	v_lshlrev_b32_e32 v12, 2, v8
	v_lshl_add_u64 v[28:29], s[72:73], 0, v[16:17]
	v_lshl_add_u64 v[20:21], s[4:5], 0, v[16:17]
	v_lshl_add_u64 v[24:25], s[88:89], 0, v[16:17]
	global_load_dwordx4 v[8:11], v12, s[18:19] offset:16
	s_nop 0
	global_load_dwordx4 v[12:15], v12, s[18:19]
	s_nop 0
	global_load_dwordx4 v[16:19], v[28:29], off nt
	s_nop 0
	global_load_dwordx4 v[20:23], v[20:21], off nt
	s_nop 0
	global_load_dwordx4 v[24:27], v[24:25], off nt
	v_add_u32_e32 v5, 0x80000, v5
	s_waitcnt vmcnt(6)
	v_lshlrev_b32_e32 v110, 16, v96
	v_and_b32_e32 v111, 0xffff0000, v96
	v_lshlrev_b32_e32 v96, 16, v97
	v_and_b32_e32 v97, 0xffff0000, v97
	v_lshlrev_b32_e32 v114, 16, v100
	v_and_b32_e32 v115, 0xffff0000, v100
	v_lshlrev_b32_e32 v100, 16, v101
	v_and_b32_e32 v101, 0xffff0000, v101
	v_lshlrev_b32_e32 v112, 16, v98
	v_and_b32_e32 v113, 0xffff0000, v98
	v_lshlrev_b32_e32 v98, 16, v99
	v_and_b32_e32 v99, 0xffff0000, v99
	v_lshlrev_b32_e32 v116, 16, v102
	v_and_b32_e32 v117, 0xffff0000, v102
	v_lshlrev_b32_e32 v102, 16, v103
	v_and_b32_e32 v103, 0xffff0000, v103
	v_pk_add_f32 v[110:111], v[110:111], v[114:115]
	v_pk_add_f32 v[96:97], v[96:97], v[100:101]
	v_pk_add_f32 v[100:101], v[112:113], v[116:117]
	v_pk_add_f32 v[98:99], v[98:99], v[102:103]
	v_pk_mul_f32 v[102:103], v[96:97], v[96:97]
	v_pk_mul_f32 v[112:113], v[110:111], v[110:111]
	v_pk_mul_f32 v[114:115], v[98:99], v[98:99]
	v_pk_mul_f32 v[116:117], v[100:101], v[100:101]
	v_pk_mov_b32 v[122:123], v[112:113], v[102:103] op_sel:[1,0]
	v_mov_b32_e32 v113, v103
	v_mov_b32_e32 v102, v114
	v_mov_b32_e32 v103, v116
	v_mov_b32_e32 v116, v115
	v_pk_add_f32 v[112:113], v[122:123], v[112:113]
	v_pk_add_f32 v[102:103], v[102:103], v[116:117]
	v_add_f32_e32 v87, v112, v113
	v_add_f32_e32 v87, v103, v87
	v_add_f32_e32 v87, v102, v87
	ds_bpermute_b32 v102, v0, v87
	v_lshlrev_b32_e32 v118, 16, v104
	v_and_b32_e32 v119, 0xffff0000, v104
	v_lshlrev_b32_e32 v104, 16, v105
	v_and_b32_e32 v105, 0xffff0000, v105
	s_waitcnt lgkmcnt(0)
	v_add_f32_e32 v87, v87, v102
	ds_bpermute_b32 v102, v1, v87
	v_lshlrev_b32_e32 v120, 16, v106
	v_and_b32_e32 v121, 0xffff0000, v106
	v_lshlrev_b32_e32 v106, 16, v107
	v_and_b32_e32 v107, 0xffff0000, v107
	s_waitcnt lgkmcnt(0)
	v_add_f32_e32 v87, v87, v102
	ds_bpermute_b32 v102, v2, v87
	s_waitcnt lgkmcnt(0)
	v_add_f32_e32 v87, v87, v102
	ds_bpermute_b32 v102, v3, v87
	s_waitcnt lgkmcnt(0)
	v_add_f32_e32 v87, v87, v102
	v_fmamk_f32 v87, v87, 0x3c000000, v6
	v_rsq_f32_e32 v102, v87
	s_nop 0
	v_pk_mul_f32 v[96:97], v[96:97], v[102:103] op_sel_hi:[1,0]
	v_pk_mul_f32 v[110:111], v[110:111], v[102:103] op_sel_hi:[1,0]
	v_pk_mul_f32 v[98:99], v[98:99], v[102:103] op_sel_hi:[1,0]
	v_pk_mul_f32 v[100:101], v[100:101], v[102:103] op_sel_hi:[1,0]
	v_pk_mul_f32 v[92:93], v[92:93], v[110:111]
	v_pk_mul_f32 v[94:95], v[94:95], v[96:97]
	v_pk_mul_f32 v[88:89], v[88:89], v[100:101]
	v_pk_mul_f32 v[90:91], v[90:91], v[98:99]
	v_pk_mul_f32 v[94:95], v[94:95], v[104:105]
	v_pk_mul_f32 v[92:93], v[92:93], v[118:119]
	v_pk_mul_f32 v[96:97], v[90:91], v[106:107]
	v_pk_mul_f32 v[90:91], v[88:89], v[120:121]
	v_cvt_pk_bf16_f32 v88, v92, v93
	v_cvt_pk_bf16_f32 v89, v94, v95
	v_cvt_pk_bf16_f32 v90, v90, v91
	v_cvt_pk_bf16_f32 v91, v96, v97
	global_store_dwordx4 v[108:109], v[88:91], off
	s_nop 1
	v_add_u32_e32 v4, 0x10000, v4
	v_ashrrev_i32_e32 v96, 7, v4
	v_ashrrev_i32_e32 v97, 31, v96
	v_and_b32_e32 v87, 0x3f8, v5
	v_lshlrev_b64 v[96:97], 11, v[96:97]
	v_and_b32_e32 v88, 0x78, v5
	v_lshl_or_b32 v96, v87, 1, v96
	v_lshlrev_b32_e32 v92, 2, v88
	v_lshl_add_u64 v[108:109], s[72:73], 0, v[96:97]
	v_lshl_add_u64 v[100:101], s[4:5], 0, v[96:97]
	v_lshl_add_u64 v[104:105], s[88:89], 0, v[96:97]
	global_load_dwordx4 v[88:91], v92, s[18:19] offset:16
	s_nop 0
	global_load_dwordx4 v[92:95], v92, s[18:19]
	s_nop 0
	global_load_dwordx4 v[96:99], v[108:109], off nt
	s_nop 0
	global_load_dwordx4 v[100:103], v[100:101], off nt
	s_nop 0
	global_load_dwordx4 v[104:107], v[104:105], off nt
	v_add_u32_e32 v5, 0x80000, v5
	s_waitcnt vmcnt(6)
	v_lshlrev_b32_e32 v30, 16, v16
	v_and_b32_e32 v31, 0xffff0000, v16
	v_lshlrev_b32_e32 v16, 16, v17
	v_and_b32_e32 v17, 0xffff0000, v17
	v_lshlrev_b32_e32 v34, 16, v20
	v_and_b32_e32 v35, 0xffff0000, v20
	v_lshlrev_b32_e32 v20, 16, v21
	v_and_b32_e32 v21, 0xffff0000, v21
	v_lshlrev_b32_e32 v32, 16, v18
	v_and_b32_e32 v33, 0xffff0000, v18
	v_lshlrev_b32_e32 v18, 16, v19
	v_and_b32_e32 v19, 0xffff0000, v19
	v_lshlrev_b32_e32 v36, 16, v22
	v_and_b32_e32 v37, 0xffff0000, v22
	v_lshlrev_b32_e32 v22, 16, v23
	v_and_b32_e32 v23, 0xffff0000, v23
	v_pk_add_f32 v[30:31], v[30:31], v[34:35]
	v_pk_add_f32 v[16:17], v[16:17], v[20:21]
	v_pk_add_f32 v[20:21], v[32:33], v[36:37]
	v_pk_add_f32 v[18:19], v[18:19], v[22:23]
	v_pk_mul_f32 v[22:23], v[16:17], v[16:17]
	v_pk_mul_f32 v[32:33], v[30:31], v[30:31]
	v_pk_mul_f32 v[34:35], v[18:19], v[18:19]
	v_pk_mul_f32 v[36:37], v[20:21], v[20:21]
	v_pk_mov_b32 v[42:43], v[32:33], v[22:23] op_sel:[1,0]
	v_mov_b32_e32 v33, v23
	v_mov_b32_e32 v22, v34
	v_mov_b32_e32 v23, v36
	v_mov_b32_e32 v36, v35
	v_pk_add_f32 v[32:33], v[42:43], v[32:33]
	v_pk_add_f32 v[22:23], v[22:23], v[36:37]
	v_add_f32_e32 v7, v32, v33
	v_add_f32_e32 v7, v23, v7
	v_add_f32_e32 v7, v22, v7
	ds_bpermute_b32 v22, v0, v7
	v_lshlrev_b32_e32 v38, 16, v24
	v_and_b32_e32 v39, 0xffff0000, v24
	v_lshlrev_b32_e32 v24, 16, v25
	v_and_b32_e32 v25, 0xffff0000, v25
	s_waitcnt lgkmcnt(0)
	v_add_f32_e32 v7, v7, v22
	ds_bpermute_b32 v22, v1, v7
	v_lshlrev_b32_e32 v40, 16, v26
	v_and_b32_e32 v41, 0xffff0000, v26
	v_lshlrev_b32_e32 v26, 16, v27
	v_and_b32_e32 v27, 0xffff0000, v27
	s_waitcnt lgkmcnt(0)
	v_add_f32_e32 v7, v7, v22
	ds_bpermute_b32 v22, v2, v7
	s_waitcnt lgkmcnt(0)
	v_add_f32_e32 v7, v7, v22
	ds_bpermute_b32 v22, v3, v7
	s_waitcnt lgkmcnt(0)
	v_add_f32_e32 v7, v7, v22
	v_fmamk_f32 v7, v7, 0x3c000000, v6
	v_rsq_f32_e32 v22, v7
	s_nop 0
	v_pk_mul_f32 v[16:17], v[16:17], v[22:23] op_sel_hi:[1,0]
	v_pk_mul_f32 v[30:31], v[30:31], v[22:23] op_sel_hi:[1,0]
	v_pk_mul_f32 v[18:19], v[18:19], v[22:23] op_sel_hi:[1,0]
	v_pk_mul_f32 v[20:21], v[20:21], v[22:23] op_sel_hi:[1,0]
	v_pk_mul_f32 v[12:13], v[12:13], v[30:31]
	v_pk_mul_f32 v[14:15], v[14:15], v[16:17]
	v_pk_mul_f32 v[8:9], v[8:9], v[20:21]
	v_pk_mul_f32 v[10:11], v[10:11], v[18:19]
	v_pk_mul_f32 v[14:15], v[14:15], v[24:25]
	v_pk_mul_f32 v[12:13], v[12:13], v[38:39]
	v_pk_mul_f32 v[16:17], v[10:11], v[26:27]
	v_pk_mul_f32 v[10:11], v[8:9], v[40:41]
	v_cvt_pk_bf16_f32 v8, v12, v13
	v_cvt_pk_bf16_f32 v9, v14, v15
	v_cvt_pk_bf16_f32 v10, v10, v11
	v_cvt_pk_bf16_f32 v11, v16, v17
	global_store_dwordx4 v[28:29], v[8:11], off
	s_nop 1
	s_waitcnt vmcnt(1)
	v_lshlrev_b32_e32 v110, 16, v96
	v_and_b32_e32 v111, 0xffff0000, v96
	v_lshlrev_b32_e32 v96, 16, v97
	v_and_b32_e32 v97, 0xffff0000, v97
	v_lshlrev_b32_e32 v114, 16, v100
	v_and_b32_e32 v115, 0xffff0000, v100
	v_lshlrev_b32_e32 v100, 16, v101
	v_and_b32_e32 v101, 0xffff0000, v101
	v_lshlrev_b32_e32 v112, 16, v98
	v_and_b32_e32 v113, 0xffff0000, v98
	v_lshlrev_b32_e32 v98, 16, v99
	v_and_b32_e32 v99, 0xffff0000, v99
	v_lshlrev_b32_e32 v116, 16, v102
	v_and_b32_e32 v117, 0xffff0000, v102
	v_lshlrev_b32_e32 v102, 16, v103
	v_and_b32_e32 v103, 0xffff0000, v103
	v_pk_add_f32 v[110:111], v[110:111], v[114:115]
	v_pk_add_f32 v[96:97], v[96:97], v[100:101]
	v_pk_add_f32 v[100:101], v[112:113], v[116:117]
	v_pk_add_f32 v[98:99], v[98:99], v[102:103]
	v_pk_mul_f32 v[102:103], v[96:97], v[96:97]
	v_pk_mul_f32 v[112:113], v[110:111], v[110:111]
	v_pk_mul_f32 v[114:115], v[98:99], v[98:99]
	v_pk_mul_f32 v[116:117], v[100:101], v[100:101]
	v_pk_mov_b32 v[122:123], v[112:113], v[102:103] op_sel:[1,0]
	v_mov_b32_e32 v113, v103
	v_mov_b32_e32 v102, v114
	v_mov_b32_e32 v103, v116
	v_mov_b32_e32 v116, v115
	v_pk_add_f32 v[112:113], v[122:123], v[112:113]
	v_pk_add_f32 v[102:103], v[102:103], v[116:117]
	v_add_f32_e32 v87, v112, v113
	v_add_f32_e32 v87, v103, v87
	v_add_f32_e32 v87, v102, v87
	ds_bpermute_b32 v102, v0, v87
	v_lshlrev_b32_e32 v118, 16, v104
	v_and_b32_e32 v119, 0xffff0000, v104
	v_lshlrev_b32_e32 v104, 16, v105
	v_and_b32_e32 v105, 0xffff0000, v105
	s_waitcnt lgkmcnt(0)
	v_add_f32_e32 v87, v87, v102
	ds_bpermute_b32 v102, v1, v87
	v_lshlrev_b32_e32 v120, 16, v106
	v_and_b32_e32 v121, 0xffff0000, v106
	v_lshlrev_b32_e32 v106, 16, v107
	v_and_b32_e32 v107, 0xffff0000, v107
	s_waitcnt lgkmcnt(0)
	v_add_f32_e32 v87, v87, v102
	ds_bpermute_b32 v102, v2, v87
	s_waitcnt lgkmcnt(0)
	v_add_f32_e32 v87, v87, v102
	ds_bpermute_b32 v102, v3, v87
	s_waitcnt lgkmcnt(0)
	v_add_f32_e32 v87, v87, v102
	v_fmamk_f32 v87, v87, 0x3c000000, v6
	v_rsq_f32_e32 v102, v87
	s_nop 0
	v_pk_mul_f32 v[96:97], v[96:97], v[102:103] op_sel_hi:[1,0]
	v_pk_mul_f32 v[110:111], v[110:111], v[102:103] op_sel_hi:[1,0]
	v_pk_mul_f32 v[98:99], v[98:99], v[102:103] op_sel_hi:[1,0]
	v_pk_mul_f32 v[100:101], v[100:101], v[102:103] op_sel_hi:[1,0]
	v_pk_mul_f32 v[92:93], v[92:93], v[110:111]
	v_pk_mul_f32 v[94:95], v[94:95], v[96:97]
	v_pk_mul_f32 v[88:89], v[88:89], v[100:101]
	v_pk_mul_f32 v[90:91], v[90:91], v[98:99]
	v_pk_mul_f32 v[94:95], v[94:95], v[104:105]
	v_pk_mul_f32 v[92:93], v[92:93], v[118:119]
	v_pk_mul_f32 v[96:97], v[90:91], v[106:107]
	v_pk_mul_f32 v[90:91], v[88:89], v[120:121]
	v_cvt_pk_bf16_f32 v88, v92, v93
	v_cvt_pk_bf16_f32 v89, v94, v95
	v_cvt_pk_bf16_f32 v90, v90, v91
	v_cvt_pk_bf16_f32 v91, v96, v97
	global_store_dwordx4 v[108:109], v[88:91], off
	s_nop 1
	s_branch .LBB0_468
